# scan consumer: the two 16-lane dot reductions merged into one DPP chain by lane parity (2 cndmask + 4 DPP instead of 8 DPP), state update via fmac_dpp; serial fmac dot chains
# baseline (speedup 1.0000x reference)
; __device__ __forceinline__ void scan_phase(const Args& a, LAS unsigned char* lds, const bf16* Z, const float* W, const bf16* Aa, const bf16* KK, float* Y, int tid, int lane, int wave) {
;     ...
;             if (consumer) {
;                 const LAS float* sb = buf + (ch & 1) * (SCH * SROW) + 4 * j;
;                 const LAS float* vb = buf + (ch & 1) * (SCH * SROW) + 320 + ri;
;                 f32x4 pw[3], pk[3], pa[3], pb[3], pr[3]; float pv[3];
; #pragma unroll
;                 for (int i = 0; i < 2; ++i) { const LAS float* p = sb + i * SROW;
;                     pw[i] = *(const LAS f32x4*)p; pk[i] = *(const LAS f32x4*)(p + 64); pa[i] = *(const LAS f32x4*)(p + 128); pb[i] = *(const LAS f32x4*)(p + 192); pr[i] = *(const LAS f32x4*)(p + 256); pv[i] = vb[i * SROW]; }
;                 float ykA = 0.f, ykB = 0.f, yd = 0.f;
; #pragma unroll
;                 for (int q = 0; q < SCH; ++q) {
;                     const f32x4 wv = pw[q % 3], kv = pk[q % 3], av = pa[q % 3], bv = pb[q % 3], rv = pr[q % 3]; const float vv = pv[q % 3];
;                     if (q + 2 < SCH) {
;                         const LAS float* p = sb + (q + 2) * SROW; const int i = (q + 2) % 3;
;                         pw[i] = *(const LAS f32x4*)p; pk[i] = *(const LAS f32x4*)(p + 64); pa[i] = *(const LAS f32x4*)(p + 128); pb[i] = *(const LAS f32x4*)(p + 192); pr[i] = *(const LAS f32x4*)(p + 256);
;                         pv[i] = vb[(q + 2) * SROW];
;                     }
;                     f32x2 t2 = S01 * (f32x2){av.x, av.y}; t2 = S23 * (f32x2){av.z, av.w} + t2;
;                     float sa = t2.x + t2.y;
;                     sa += dppf<0xB1>(sa); yd += dppf<0xB1>(yd);
;                     sa += dppf<0x4E>(sa); yd += dppf<0x4E>(yd);
;                     sa += dppf<0x141>(sa); yd += dppf<0x141>(yd);
;                     sa += dppf<0x140>(sa); yd += dppf<0x140>(yd);
;                     if (q > 0) { if (q <= 16) ykA = (j == q - 1) ? yd : ykA; else ykB = (j == q - 17) ? yd : ykB; }
;                     const f32x2 u01 = S01 * (f32x2){wv.x, wv.y} + (f32x2){kv.x, kv.y} * vv, u23 = S23 * (f32x2){wv.z, wv.w} + (f32x2){kv.z, kv.w} * vv;
;                     S01 = u01 + (f32x2){bv.x, bv.y} * sa; S23 = u23 + (f32x2){bv.z, bv.w} * sa;
;                     f32x2 y2 = S01 * (f32x2){rv.x, rv.y}; y2 = S23 * (f32x2){rv.z, rv.w} + y2;
;                     yd = y2.x + y2.y;
.LBB0_283:
	s_andn2_b64 vcc, exec, s[12:13]
	s_cbranch_vccnz .LBB0_224
	s_mov_b32 s100, 0x55555555
	s_mov_b32 s101, 0x55555555
	s_bitcmp1_b32 s22, 0
	s_cselect_b32 s16, 0xa800, 0
	s_add_i32 s16, s16, 0
	v_add_u32_e32 v195, s16, v123
	v_lshl_add_u32 v127, v126, 2, s16
	ds_read_b128 v[64:67], v195
	ds_read_b128 v[68:71], v195 offset:256
	ds_read_b128 v[72:75], v195 offset:512
	ds_read_b128 v[76:79], v195 offset:768
	ds_read_b128 v[80:83], v195 offset:1024
	ds_read_b32 v62, v127 offset:1280
	ds_read_b128 v[84:87], v195 offset:1344
	ds_read_b128 v[88:91], v195 offset:1600
	ds_read_b128 v[92:95], v195 offset:1856
	ds_read_b128 v[96:99], v195 offset:2112
	ds_read_b128 v[100:103], v195 offset:2368
	ds_read_b32 v63, v127 offset:2624
	s_waitcnt lgkmcnt(6)
	v_mul_f32_e32 v204, v58, v72
	v_fmac_f32_e32 v204, v59, v73
	v_fmac_f32_e32 v204, v60, v74
	v_fmac_f32_e32 v204, v61, v75
	v_mul_f32_e32 v208, v58, v64
	v_mul_f32_e32 v209, v59, v65
	v_add_f32_dpp v204, v204, v204 quad_perm:[1,0,3,2] row_mask:0xf bank_mask:0xf bound_ctrl:1
	v_mul_f32_e32 v210, v60, v66
	v_mul_f32_e32 v211, v61, v67
	v_add_f32_dpp v204, v204, v204 quad_perm:[2,3,0,1] row_mask:0xf bank_mask:0xf bound_ctrl:1
	v_fmac_f32_e32 v208, v68, v62
	v_fmac_f32_e32 v209, v69, v62
	v_add_f32_dpp v204, v204, v204 row_half_mirror row_mask:0xf bank_mask:0xf bound_ctrl:1
	v_fmac_f32_e32 v210, v70, v62
	v_fmac_f32_e32 v211, v71, v62
	v_add_f32_dpp v204, v204, v204 row_mirror row_mask:0xf bank_mask:0xf bound_ctrl:1
	ds_read_b128 v[104:107], v195 offset:2688
	ds_read_b128 v[108:111], v195 offset:2944
	ds_read_b128 v[112:115], v195 offset:3200
	ds_read_b128 v[196:199], v195 offset:3456
	ds_read_b128 v[200:203], v195 offset:3712
	ds_read_b32 v182, v127 offset:3968
	v_fmac_f32_e32 v208, v76, v204
	v_fmac_f32_e32 v209, v77, v204
	v_fmac_f32_e32 v210, v78, v204
	v_fmac_f32_e32 v211, v79, v204
	s_waitcnt lgkmcnt(6)
	v_mul_f32_e32 v204, v208, v92
	v_mul_f32_e32 v212, v208, v80
	v_fmac_f32_e32 v204, v209, v93
	v_fmac_f32_e32 v212, v209, v81
	v_fmac_f32_e32 v204, v210, v94
	v_fmac_f32_e32 v212, v210, v82
	v_fmac_f32_e32 v204, v211, v95
	v_fmac_f32_e32 v212, v211, v83
	v_mul_f32_e32 v58, v208, v84
	v_mul_f32_e32 v59, v209, v85
	v_mul_f32_e32 v60, v210, v86
	v_cndmask_b32_e64 v205, v212, v204, s[100:101]
	v_cndmask_b32_e64 v213, v204, v212, s[100:101]
	v_mul_f32_e32 v61, v211, v87
	v_add_f32_dpp v204, v205, v213 quad_perm:[1,0,3,2] row_mask:0xf bank_mask:0xf bound_ctrl:1
	v_fmac_f32_e32 v58, v88, v63
	v_fmac_f32_e32 v59, v89, v63
	v_add_f32_dpp v204, v204, v204 quad_perm:[2,3,0,1] row_mask:0xf bank_mask:0xf bound_ctrl:1
	v_fmac_f32_e32 v60, v90, v63
	v_fmac_f32_e32 v61, v91, v63
	v_add_f32_dpp v204, v204, v204 row_ror:4 row_mask:0xf bank_mask:0xf bound_ctrl:1
	ds_read_b128 v[64:67], v195 offset:4032
	ds_read_b128 v[68:71], v195 offset:4288
	v_add_f32_dpp v204, v204, v204 row_ror:8 row_mask:0xf bank_mask:0xf bound_ctrl:1
	ds_read_b128 v[72:75], v195 offset:4544
	ds_read_b128 v[76:79], v195 offset:4800
	ds_read_b128 v[80:83], v195 offset:5056
	ds_read_b32 v62, v127 offset:5312
	v_fmac_f32_dpp v58, v204, v96 quad_perm:[1,1,3,3] row_mask:0xf bank_mask:0xf
	v_fmac_f32_dpp v59, v204, v97 quad_perm:[1,1,3,3] row_mask:0xf bank_mask:0xf
	v_fmac_f32_dpp v60, v204, v98 quad_perm:[1,1,3,3] row_mask:0xf bank_mask:0xf
	v_fmac_f32_dpp v61, v204, v99 quad_perm:[1,1,3,3] row_mask:0xf bank_mask:0xf
	v_cndmask_b32_e64 v214, 0, v204, s[82:83]
	s_waitcnt lgkmcnt(6)
	v_mul_f32_e32 v204, v58, v112
	v_mul_f32_e32 v212, v58, v100
	v_fmac_f32_e32 v204, v59, v113
	v_fmac_f32_e32 v212, v59, v101
	v_fmac_f32_e32 v204, v60, v114
	v_fmac_f32_e32 v212, v60, v102
	v_fmac_f32_e32 v204, v61, v115
	v_fmac_f32_e32 v212, v61, v103
	v_mul_f32_e32 v208, v58, v104
	v_mul_f32_e32 v209, v59, v105
	v_mul_f32_e32 v210, v60, v106
	v_cndmask_b32_e64 v205, v204, v212, s[100:101]
	v_cndmask_b32_e64 v213, v212, v204, s[100:101]
	v_mul_f32_e32 v211, v61, v107
	v_add_f32_dpp v204, v205, v213 quad_perm:[1,0,3,2] row_mask:0xf bank_mask:0xf bound_ctrl:1
	v_fmac_f32_e32 v208, v108, v182
	v_fmac_f32_e32 v209, v109, v182
	v_add_f32_dpp v204, v204, v204 quad_perm:[2,3,0,1] row_mask:0xf bank_mask:0xf bound_ctrl:1
	v_fmac_f32_e32 v210, v110, v182
	v_fmac_f32_e32 v211, v111, v182
	v_add_f32_dpp v204, v204, v204 row_ror:4 row_mask:0xf bank_mask:0xf bound_ctrl:1
	ds_read_b128 v[84:87], v195 offset:5376
	ds_read_b128 v[88:91], v195 offset:5632
	v_add_f32_dpp v204, v204, v204 row_ror:8 row_mask:0xf bank_mask:0xf bound_ctrl:1
	ds_read_b128 v[92:95], v195 offset:5888
	ds_read_b128 v[96:99], v195 offset:6144
	ds_read_b128 v[100:103], v195 offset:6400
	ds_read_b32 v63, v127 offset:6656
	v_fmac_f32_dpp v208, v204, v196 quad_perm:[0,0,2,2] row_mask:0xf bank_mask:0xf
	v_fmac_f32_dpp v209, v204, v197 quad_perm:[0,0,2,2] row_mask:0xf bank_mask:0xf
	v_fmac_f32_dpp v210, v204, v198 quad_perm:[0,0,2,2] row_mask:0xf bank_mask:0xf
	v_fmac_f32_dpp v211, v204, v199 quad_perm:[0,0,2,2] row_mask:0xf bank_mask:0xf
	v_cndmask_b32_e64 v214, v214, v204, s[80:81]
	s_waitcnt lgkmcnt(6)
; #define LAS __attribute__((address_space(3)))
; template <int CTRL> __device__ __forceinline__ float dppf(float v) { return __int_as_float(__builtin_amdgcn_update_dpp(0, __float_as_int(v), CTRL, 0xf, 0xf, true)); }
; __device__ __forceinline__ void scan_phase(const Args& a, LAS unsigned char* lds, const bf16* Z, const float* W, const bf16* Aa, const bf16* KK, float* Y, int tid, int lane, int wave) {
;     ...
;                 for (int q = 0; q < SCH; ++q) {
;                     const f32x4 wv = pw[q % 3], kv = pk[q % 3], av = pa[q % 3], bv = pb[q % 3], rv = pr[q % 3]; const float vv = pv[q % 3];
;                     if (q + 2 < SCH) {
;                         const LAS float* p = sb + (q + 2) * SROW; const int i = (q + 2) % 3;
;                         pw[i] = *(const LAS f32x4*)p; pk[i] = *(const LAS f32x4*)(p + 64); pa[i] = *(const LAS f32x4*)(p + 128); pb[i] = *(const LAS f32x4*)(p + 192); pr[i] = *(const LAS f32x4*)(p + 256);
;                         pv[i] = vb[(q + 2) * SROW];
;                     }
;                     f32x2 t2 = S01 * (f32x2){av.x, av.y}; t2 = S23 * (f32x2){av.z, av.w} + t2;
;                     float sa = t2.x + t2.y;
;                     sa += dppf<0xB1>(sa); yd += dppf<0xB1>(yd);
;                     sa += dppf<0x4E>(sa); yd += dppf<0x4E>(yd);
;                     sa += dppf<0x141>(sa); yd += dppf<0x141>(yd);
;                     sa += dppf<0x140>(sa); yd += dppf<0x140>(yd);
;                     if (q > 0) { if (q <= 16) ykA = (j == q - 1) ? yd : ykA; else ykB = (j == q - 17) ? yd : ykB; }
;                     const f32x2 u01 = S01 * (f32x2){wv.x, wv.y} + (f32x2){kv.x, kv.y} * vv, u23 = S23 * (f32x2){wv.z, wv.w} + (f32x2){kv.z, kv.w} * vv;
;                     S01 = u01 + (f32x2){bv.x, bv.y} * sa; S23 = u23 + (f32x2){bv.z, bv.w} * sa;
;                     f32x2 y2 = S01 * (f32x2){rv.x, rv.y}; y2 = S23 * (f32x2){rv.z, rv.w} + y2;
;                     yd = y2.x + y2.y;
;                 }
	v_mul_f32_e32 v204, v208, v72
	v_mul_f32_e32 v212, v208, v200
	v_fmac_f32_e32 v204, v209, v73
	v_fmac_f32_e32 v212, v209, v201
	v_fmac_f32_e32 v204, v210, v74
	v_fmac_f32_e32 v212, v210, v202
	v_fmac_f32_e32 v204, v211, v75
	v_fmac_f32_e32 v212, v211, v203
	v_mul_f32_e32 v58, v208, v64
	v_mul_f32_e32 v59, v209, v65
	v_mul_f32_e32 v60, v210, v66
	v_cndmask_b32_e64 v205, v212, v204, s[100:101]
	v_cndmask_b32_e64 v213, v204, v212, s[100:101]
	v_mul_f32_e32 v61, v211, v67
	v_add_f32_dpp v204, v205, v213 quad_perm:[1,0,3,2] row_mask:0xf bank_mask:0xf bound_ctrl:1
	v_fmac_f32_e32 v58, v68, v62
	v_fmac_f32_e32 v59, v69, v62
	v_add_f32_dpp v204, v204, v204 quad_perm:[2,3,0,1] row_mask:0xf bank_mask:0xf bound_ctrl:1
	v_fmac_f32_e32 v60, v70, v62
	v_fmac_f32_e32 v61, v71, v62
	v_add_f32_dpp v204, v204, v204 row_ror:4 row_mask:0xf bank_mask:0xf bound_ctrl:1
	ds_read_b128 v[104:107], v195 offset:6720
	ds_read_b128 v[108:111], v195 offset:6976
	v_add_f32_dpp v204, v204, v204 row_ror:8 row_mask:0xf bank_mask:0xf bound_ctrl:1
	ds_read_b128 v[112:115], v195 offset:7232
	ds_read_b128 v[196:199], v195 offset:7488
	ds_read_b128 v[200:203], v195 offset:7744
	ds_read_b32 v182, v127 offset:8000
	v_fmac_f32_dpp v58, v204, v76 quad_perm:[1,1,3,3] row_mask:0xf bank_mask:0xf
	v_fmac_f32_dpp v59, v204, v77 quad_perm:[1,1,3,3] row_mask:0xf bank_mask:0xf
	v_fmac_f32_dpp v60, v204, v78 quad_perm:[1,1,3,3] row_mask:0xf bank_mask:0xf
	v_fmac_f32_dpp v61, v204, v79 quad_perm:[1,1,3,3] row_mask:0xf bank_mask:0xf
	v_cndmask_b32_e64 v214, v214, v204, s[6:7]
	s_waitcnt lgkmcnt(6)
	v_mul_f32_e32 v204, v58, v92
	v_mul_f32_e32 v212, v58, v80
	v_fmac_f32_e32 v204, v59, v93
	v_fmac_f32_e32 v212, v59, v81
	v_fmac_f32_e32 v204, v60, v94
	v_fmac_f32_e32 v212, v60, v82
	v_fmac_f32_e32 v204, v61, v95
	v_fmac_f32_e32 v212, v61, v83
	v_mul_f32_e32 v208, v58, v84
	v_mul_f32_e32 v209, v59, v85
	v_mul_f32_e32 v210, v60, v86
	v_cndmask_b32_e64 v205, v204, v212, s[100:101]
	v_cndmask_b32_e64 v213, v212, v204, s[100:101]
	v_mul_f32_e32 v211, v61, v87
	v_add_f32_dpp v204, v205, v213 quad_perm:[1,0,3,2] row_mask:0xf bank_mask:0xf bound_ctrl:1
	v_fmac_f32_e32 v208, v88, v63
	v_fmac_f32_e32 v209, v89, v63
	v_add_f32_dpp v204, v204, v204 quad_perm:[2,3,0,1] row_mask:0xf bank_mask:0xf bound_ctrl:1
	v_fmac_f32_e32 v210, v90, v63
	v_fmac_f32_e32 v211, v91, v63
	v_add_f32_dpp v204, v204, v204 row_ror:4 row_mask:0xf bank_mask:0xf bound_ctrl:1
	ds_read_b128 v[64:67], v195 offset:8064
	ds_read_b128 v[68:71], v195 offset:8320
	v_add_f32_dpp v204, v204, v204 row_ror:8 row_mask:0xf bank_mask:0xf bound_ctrl:1
	ds_read_b128 v[72:75], v195 offset:8576
	ds_read_b128 v[76:79], v195 offset:8832
	ds_read_b128 v[80:83], v195 offset:9088
	ds_read_b32 v62, v127 offset:9344
	v_fmac_f32_dpp v208, v204, v96 quad_perm:[0,0,2,2] row_mask:0xf bank_mask:0xf
	v_fmac_f32_dpp v209, v204, v97 quad_perm:[0,0,2,2] row_mask:0xf bank_mask:0xf
	v_fmac_f32_dpp v210, v204, v98 quad_perm:[0,0,2,2] row_mask:0xf bank_mask:0xf
	v_fmac_f32_dpp v211, v204, v99 quad_perm:[0,0,2,2] row_mask:0xf bank_mask:0xf
	v_cndmask_b32_e64 v214, v214, v204, s[8:9]
	s_waitcnt lgkmcnt(6)
	v_mul_f32_e32 v204, v208, v112
	v_mul_f32_e32 v212, v208, v100
	v_fmac_f32_e32 v204, v209, v113
	v_fmac_f32_e32 v212, v209, v101
	v_fmac_f32_e32 v204, v210, v114
	v_fmac_f32_e32 v212, v210, v102
	v_fmac_f32_e32 v204, v211, v115
	v_fmac_f32_e32 v212, v211, v103
	v_mul_f32_e32 v58, v208, v104
	v_mul_f32_e32 v59, v209, v105
	v_mul_f32_e32 v60, v210, v106
	v_cndmask_b32_e64 v205, v212, v204, s[100:101]
	v_cndmask_b32_e64 v213, v204, v212, s[100:101]
	v_mul_f32_e32 v61, v211, v107
	v_add_f32_dpp v204, v205, v213 quad_perm:[1,0,3,2] row_mask:0xf bank_mask:0xf bound_ctrl:1
	v_fmac_f32_e32 v58, v108, v182
	v_fmac_f32_e32 v59, v109, v182
	v_add_f32_dpp v204, v204, v204 quad_perm:[2,3,0,1] row_mask:0xf bank_mask:0xf bound_ctrl:1
	v_fmac_f32_e32 v60, v110, v182
	v_fmac_f32_e32 v61, v111, v182
	v_add_f32_dpp v204, v204, v204 row_ror:4 row_mask:0xf bank_mask:0xf bound_ctrl:1
	ds_read_b128 v[84:87], v195 offset:9408
	ds_read_b128 v[88:91], v195 offset:9664
	v_add_f32_dpp v204, v204, v204 row_ror:8 row_mask:0xf bank_mask:0xf bound_ctrl:1
	ds_read_b128 v[92:95], v195 offset:9920
	ds_read_b128 v[96:99], v195 offset:10176
	ds_read_b128 v[100:103], v195 offset:10432
	ds_read_b32 v63, v127 offset:10688
	v_fmac_f32_dpp v58, v204, v196 quad_perm:[1,1,3,3] row_mask:0xf bank_mask:0xf
	v_fmac_f32_dpp v59, v204, v197 quad_perm:[1,1,3,3] row_mask:0xf bank_mask:0xf
	v_fmac_f32_dpp v60, v204, v198 quad_perm:[1,1,3,3] row_mask:0xf bank_mask:0xf
	v_fmac_f32_dpp v61, v204, v199 quad_perm:[1,1,3,3] row_mask:0xf bank_mask:0xf
	v_cndmask_b32_e64 v214, v214, v204, s[10:11]
	s_waitcnt lgkmcnt(6)
	v_mul_f32_e32 v204, v58, v72
	v_mul_f32_e32 v212, v58, v200
	v_fmac_f32_e32 v204, v59, v73
	v_fmac_f32_e32 v212, v59, v201
	v_fmac_f32_e32 v204, v60, v74
	v_fmac_f32_e32 v212, v60, v202
	v_fmac_f32_e32 v204, v61, v75
	v_fmac_f32_e32 v212, v61, v203
	v_mul_f32_e32 v208, v58, v64
	v_mul_f32_e32 v209, v59, v65
	v_mul_f32_e32 v210, v60, v66
	v_cndmask_b32_e64 v205, v204, v212, s[100:101]
	v_cndmask_b32_e64 v213, v212, v204, s[100:101]
	v_mul_f32_e32 v211, v61, v67
	v_add_f32_dpp v204, v205, v213 quad_perm:[1,0,3,2] row_mask:0xf bank_mask:0xf bound_ctrl:1
	v_fmac_f32_e32 v208, v68, v62
	v_fmac_f32_e32 v209, v69, v62
	v_add_f32_dpp v204, v204, v204 quad_perm:[2,3,0,1] row_mask:0xf bank_mask:0xf bound_ctrl:1
	v_fmac_f32_e32 v210, v70, v62
	v_fmac_f32_e32 v211, v71, v62
	v_add_f32_dpp v204, v204, v204 row_ror:4 row_mask:0xf bank_mask:0xf bound_ctrl:1
	ds_read_b128 v[104:107], v195 offset:10752
	ds_read_b128 v[108:111], v195 offset:11008
	v_add_f32_dpp v204, v204, v204 row_ror:8 row_mask:0xf bank_mask:0xf bound_ctrl:1
	ds_read_b128 v[112:115], v195 offset:11264
	ds_read_b128 v[196:199], v195 offset:11520
	ds_read_b128 v[200:203], v195 offset:11776
	ds_read_b32 v182, v127 offset:12032
	v_fmac_f32_dpp v208, v204, v76 quad_perm:[0,0,2,2] row_mask:0xf bank_mask:0xf
	v_fmac_f32_dpp v209, v204, v77 quad_perm:[0,0,2,2] row_mask:0xf bank_mask:0xf
	v_fmac_f32_dpp v210, v204, v78 quad_perm:[0,0,2,2] row_mask:0xf bank_mask:0xf
	v_fmac_f32_dpp v211, v204, v79 quad_perm:[0,0,2,2] row_mask:0xf bank_mask:0xf
	v_cndmask_b32_e64 v214, v214, v204, s[90:91]
	s_waitcnt lgkmcnt(6)
; #define LAS __attribute__((address_space(3)))
; template <int CTRL> __device__ __forceinline__ float dppf(float v) { return __int_as_float(__builtin_amdgcn_update_dpp(0, __float_as_int(v), CTRL, 0xf, 0xf, true)); }
; __device__ __forceinline__ void scan_phase(const Args& a, LAS unsigned char* lds, const bf16* Z, const float* W, const bf16* Aa, const bf16* KK, float* Y, int tid, int lane, int wave) {
;     ...
;                 for (int q = 0; q < SCH; ++q) {
;                     const f32x4 wv = pw[q % 3], kv = pk[q % 3], av = pa[q % 3], bv = pb[q % 3], rv = pr[q % 3]; const float vv = pv[q % 3];
;                     if (q + 2 < SCH) {
;                         const LAS float* p = sb + (q + 2) * SROW; const int i = (q + 2) % 3;
;                         pw[i] = *(const LAS f32x4*)p; pk[i] = *(const LAS f32x4*)(p + 64); pa[i] = *(const LAS f32x4*)(p + 128); pb[i] = *(const LAS f32x4*)(p + 192); pr[i] = *(const LAS f32x4*)(p + 256);
;                         pv[i] = vb[(q + 2) * SROW];
;                     }
;                     f32x2 t2 = S01 * (f32x2){av.x, av.y}; t2 = S23 * (f32x2){av.z, av.w} + t2;
;                     float sa = t2.x + t2.y;
;                     sa += dppf<0xB1>(sa); yd += dppf<0xB1>(yd);
;                     sa += dppf<0x4E>(sa); yd += dppf<0x4E>(yd);
;                     sa += dppf<0x141>(sa); yd += dppf<0x141>(yd);
;                     sa += dppf<0x140>(sa); yd += dppf<0x140>(yd);
;                     if (q > 0) { if (q <= 16) ykA = (j == q - 1) ? yd : ykA; else ykB = (j == q - 17) ? yd : ykB; }
;                     const f32x2 u01 = S01 * (f32x2){wv.x, wv.y} + (f32x2){kv.x, kv.y} * vv, u23 = S23 * (f32x2){wv.z, wv.w} + (f32x2){kv.z, kv.w} * vv;
;                     S01 = u01 + (f32x2){bv.x, bv.y} * sa; S23 = u23 + (f32x2){bv.z, bv.w} * sa;
;                     f32x2 y2 = S01 * (f32x2){rv.x, rv.y}; y2 = S23 * (f32x2){rv.z, rv.w} + y2;
;                     yd = y2.x + y2.y;
;                 }
	v_mul_f32_e32 v204, v208, v92
	v_mul_f32_e32 v212, v208, v80
	v_fmac_f32_e32 v204, v209, v93
	v_fmac_f32_e32 v212, v209, v81
	v_fmac_f32_e32 v204, v210, v94
	v_fmac_f32_e32 v212, v210, v82
	v_fmac_f32_e32 v204, v211, v95
	v_fmac_f32_e32 v212, v211, v83
	v_mul_f32_e32 v58, v208, v84
	v_mul_f32_e32 v59, v209, v85
	v_mul_f32_e32 v60, v210, v86
	v_cndmask_b32_e64 v205, v212, v204, s[100:101]
	v_cndmask_b32_e64 v213, v204, v212, s[100:101]
	v_mul_f32_e32 v61, v211, v87
	v_add_f32_dpp v204, v205, v213 quad_perm:[1,0,3,2] row_mask:0xf bank_mask:0xf bound_ctrl:1
	v_fmac_f32_e32 v58, v88, v63
	v_fmac_f32_e32 v59, v89, v63
	v_add_f32_dpp v204, v204, v204 quad_perm:[2,3,0,1] row_mask:0xf bank_mask:0xf bound_ctrl:1
	v_fmac_f32_e32 v60, v90, v63
	v_fmac_f32_e32 v61, v91, v63
	v_add_f32_dpp v204, v204, v204 row_ror:4 row_mask:0xf bank_mask:0xf bound_ctrl:1
	ds_read_b128 v[64:67], v195 offset:12096
	ds_read_b128 v[68:71], v195 offset:12352
	v_add_f32_dpp v204, v204, v204 row_ror:8 row_mask:0xf bank_mask:0xf bound_ctrl:1
	ds_read_b128 v[72:75], v195 offset:12608
	ds_read_b128 v[76:79], v195 offset:12864
	ds_read_b128 v[80:83], v195 offset:13120
	ds_read_b32 v62, v127 offset:13376
	v_fmac_f32_dpp v58, v204, v96 quad_perm:[1,1,3,3] row_mask:0xf bank_mask:0xf
	v_fmac_f32_dpp v59, v204, v97 quad_perm:[1,1,3,3] row_mask:0xf bank_mask:0xf
	v_fmac_f32_dpp v60, v204, v98 quad_perm:[1,1,3,3] row_mask:0xf bank_mask:0xf
	v_fmac_f32_dpp v61, v204, v99 quad_perm:[1,1,3,3] row_mask:0xf bank_mask:0xf
	v_cndmask_b32_e64 v214, v214, v204, s[60:61]
	s_waitcnt lgkmcnt(6)
	v_mul_f32_e32 v204, v58, v112
	v_mul_f32_e32 v212, v58, v100
	v_fmac_f32_e32 v204, v59, v113
	v_fmac_f32_e32 v212, v59, v101
	v_fmac_f32_e32 v204, v60, v114
	v_fmac_f32_e32 v212, v60, v102
	v_fmac_f32_e32 v204, v61, v115
	v_fmac_f32_e32 v212, v61, v103
	v_mul_f32_e32 v208, v58, v104
	v_mul_f32_e32 v209, v59, v105
	v_mul_f32_e32 v210, v60, v106
	v_cndmask_b32_e64 v205, v204, v212, s[100:101]
	v_cndmask_b32_e64 v213, v212, v204, s[100:101]
	v_mul_f32_e32 v211, v61, v107
	v_add_f32_dpp v204, v205, v213 quad_perm:[1,0,3,2] row_mask:0xf bank_mask:0xf bound_ctrl:1
	v_fmac_f32_e32 v208, v108, v182
	v_fmac_f32_e32 v209, v109, v182
	v_add_f32_dpp v204, v204, v204 quad_perm:[2,3,0,1] row_mask:0xf bank_mask:0xf bound_ctrl:1
	v_fmac_f32_e32 v210, v110, v182
	v_fmac_f32_e32 v211, v111, v182
	v_add_f32_dpp v204, v204, v204 row_ror:4 row_mask:0xf bank_mask:0xf bound_ctrl:1
	ds_read_b128 v[84:87], v195 offset:13440
	ds_read_b128 v[88:91], v195 offset:13696
	v_add_f32_dpp v204, v204, v204 row_ror:8 row_mask:0xf bank_mask:0xf bound_ctrl:1
	ds_read_b128 v[92:95], v195 offset:13952
	ds_read_b128 v[96:99], v195 offset:14208
	ds_read_b128 v[100:103], v195 offset:14464
	ds_read_b32 v63, v127 offset:14720
	v_fmac_f32_dpp v208, v204, v196 quad_perm:[0,0,2,2] row_mask:0xf bank_mask:0xf
	v_fmac_f32_dpp v209, v204, v197 quad_perm:[0,0,2,2] row_mask:0xf bank_mask:0xf
	v_fmac_f32_dpp v210, v204, v198 quad_perm:[0,0,2,2] row_mask:0xf bank_mask:0xf
	v_fmac_f32_dpp v211, v204, v199 quad_perm:[0,0,2,2] row_mask:0xf bank_mask:0xf
	v_cndmask_b32_e64 v214, v214, v204, s[62:63]
	s_waitcnt lgkmcnt(6)
	v_mul_f32_e32 v204, v208, v72
	v_mul_f32_e32 v212, v208, v200
	v_fmac_f32_e32 v204, v209, v73
	v_fmac_f32_e32 v212, v209, v201
	v_fmac_f32_e32 v204, v210, v74
	v_fmac_f32_e32 v212, v210, v202
	v_fmac_f32_e32 v204, v211, v75
	v_fmac_f32_e32 v212, v211, v203
	v_mul_f32_e32 v58, v208, v64
	v_mul_f32_e32 v59, v209, v65
	v_mul_f32_e32 v60, v210, v66
	v_cndmask_b32_e64 v205, v212, v204, s[100:101]
	v_cndmask_b32_e64 v213, v204, v212, s[100:101]
	v_mul_f32_e32 v61, v211, v67
	v_add_f32_dpp v204, v205, v213 quad_perm:[1,0,3,2] row_mask:0xf bank_mask:0xf bound_ctrl:1
	v_fmac_f32_e32 v58, v68, v62
	v_fmac_f32_e32 v59, v69, v62
	v_add_f32_dpp v204, v204, v204 quad_perm:[2,3,0,1] row_mask:0xf bank_mask:0xf bound_ctrl:1
	v_fmac_f32_e32 v60, v70, v62
	v_fmac_f32_e32 v61, v71, v62
	v_add_f32_dpp v204, v204, v204 row_ror:4 row_mask:0xf bank_mask:0xf bound_ctrl:1
	ds_read_b128 v[104:107], v195 offset:14784
	ds_read_b128 v[108:111], v195 offset:15040
	v_add_f32_dpp v204, v204, v204 row_ror:8 row_mask:0xf bank_mask:0xf bound_ctrl:1
	ds_read_b128 v[112:115], v195 offset:15296
	ds_read_b128 v[196:199], v195 offset:15552
	ds_read_b128 v[200:203], v195 offset:15808
	ds_read_b32 v182, v127 offset:16064
	v_fmac_f32_dpp v58, v204, v76 quad_perm:[1,1,3,3] row_mask:0xf bank_mask:0xf
	v_fmac_f32_dpp v59, v204, v77 quad_perm:[1,1,3,3] row_mask:0xf bank_mask:0xf
	v_fmac_f32_dpp v60, v204, v78 quad_perm:[1,1,3,3] row_mask:0xf bank_mask:0xf
	v_fmac_f32_dpp v61, v204, v79 quad_perm:[1,1,3,3] row_mask:0xf bank_mask:0xf
	v_cndmask_b32_e64 v214, v214, v204, s[64:65]
	s_waitcnt lgkmcnt(6)
	v_mul_f32_e32 v204, v58, v92
	v_mul_f32_e32 v212, v58, v80
	v_fmac_f32_e32 v204, v59, v93
	v_fmac_f32_e32 v212, v59, v81
	v_fmac_f32_e32 v204, v60, v94
	v_fmac_f32_e32 v212, v60, v82
	v_fmac_f32_e32 v204, v61, v95
	v_fmac_f32_e32 v212, v61, v83
	v_mul_f32_e32 v208, v58, v84
	v_mul_f32_e32 v209, v59, v85
	v_mul_f32_e32 v210, v60, v86
	v_cndmask_b32_e64 v205, v204, v212, s[100:101]
	v_cndmask_b32_e64 v213, v212, v204, s[100:101]
	v_mul_f32_e32 v211, v61, v87
	v_add_f32_dpp v204, v205, v213 quad_perm:[1,0,3,2] row_mask:0xf bank_mask:0xf bound_ctrl:1
	v_fmac_f32_e32 v208, v88, v63
	v_fmac_f32_e32 v209, v89, v63
	v_add_f32_dpp v204, v204, v204 quad_perm:[2,3,0,1] row_mask:0xf bank_mask:0xf bound_ctrl:1
	v_fmac_f32_e32 v210, v90, v63
	v_fmac_f32_e32 v211, v91, v63
	v_add_f32_dpp v204, v204, v204 row_ror:4 row_mask:0xf bank_mask:0xf bound_ctrl:1
	ds_read_b128 v[64:67], v195 offset:16128
	ds_read_b128 v[68:71], v195 offset:16384
	v_add_f32_dpp v204, v204, v204 row_ror:8 row_mask:0xf bank_mask:0xf bound_ctrl:1
	ds_read_b128 v[72:75], v195 offset:16640
	ds_read_b128 v[76:79], v195 offset:16896
	ds_read_b128 v[80:83], v195 offset:17152
	ds_read_b32 v62, v127 offset:17408
	v_fmac_f32_dpp v208, v204, v96 quad_perm:[0,0,2,2] row_mask:0xf bank_mask:0xf
	v_fmac_f32_dpp v209, v204, v97 quad_perm:[0,0,2,2] row_mask:0xf bank_mask:0xf
	v_fmac_f32_dpp v210, v204, v98 quad_perm:[0,0,2,2] row_mask:0xf bank_mask:0xf
	v_fmac_f32_dpp v211, v204, v99 quad_perm:[0,0,2,2] row_mask:0xf bank_mask:0xf
	v_cndmask_b32_e64 v214, v214, v204, s[66:67]
	s_waitcnt lgkmcnt(6)
; #define LAS __attribute__((address_space(3)))
; template <int CTRL> __device__ __forceinline__ float dppf(float v) { return __int_as_float(__builtin_amdgcn_update_dpp(0, __float_as_int(v), CTRL, 0xf, 0xf, true)); }
; __device__ __forceinline__ void scan_phase(const Args& a, LAS unsigned char* lds, const bf16* Z, const float* W, const bf16* Aa, const bf16* KK, float* Y, int tid, int lane, int wave) {
;     ...
;                 for (int q = 0; q < SCH; ++q) {
;                     const f32x4 wv = pw[q % 3], kv = pk[q % 3], av = pa[q % 3], bv = pb[q % 3], rv = pr[q % 3]; const float vv = pv[q % 3];
;                     if (q + 2 < SCH) {
;                         const LAS float* p = sb + (q + 2) * SROW; const int i = (q + 2) % 3;
;                         pw[i] = *(const LAS f32x4*)p; pk[i] = *(const LAS f32x4*)(p + 64); pa[i] = *(const LAS f32x4*)(p + 128); pb[i] = *(const LAS f32x4*)(p + 192); pr[i] = *(const LAS f32x4*)(p + 256);
;                         pv[i] = vb[(q + 2) * SROW];
;                     }
;                     f32x2 t2 = S01 * (f32x2){av.x, av.y}; t2 = S23 * (f32x2){av.z, av.w} + t2;
;                     float sa = t2.x + t2.y;
;                     sa += dppf<0xB1>(sa); yd += dppf<0xB1>(yd);
;                     sa += dppf<0x4E>(sa); yd += dppf<0x4E>(yd);
;                     sa += dppf<0x141>(sa); yd += dppf<0x141>(yd);
;                     sa += dppf<0x140>(sa); yd += dppf<0x140>(yd);
;                     if (q > 0) { if (q <= 16) ykA = (j == q - 1) ? yd : ykA; else ykB = (j == q - 17) ? yd : ykB; }
;                     const f32x2 u01 = S01 * (f32x2){wv.x, wv.y} + (f32x2){kv.x, kv.y} * vv, u23 = S23 * (f32x2){wv.z, wv.w} + (f32x2){kv.z, kv.w} * vv;
;                     S01 = u01 + (f32x2){bv.x, bv.y} * sa; S23 = u23 + (f32x2){bv.z, bv.w} * sa;
;                     f32x2 y2 = S01 * (f32x2){rv.x, rv.y}; y2 = S23 * (f32x2){rv.z, rv.w} + y2;
;                     yd = y2.x + y2.y;
;                 }
	v_mul_f32_e32 v204, v208, v112
	v_mul_f32_e32 v212, v208, v100
	v_fmac_f32_e32 v204, v209, v113
	v_fmac_f32_e32 v212, v209, v101
	v_fmac_f32_e32 v204, v210, v114
	v_fmac_f32_e32 v212, v210, v102
	v_fmac_f32_e32 v204, v211, v115
	v_fmac_f32_e32 v212, v211, v103
	v_mul_f32_e32 v58, v208, v104
	v_mul_f32_e32 v59, v209, v105
	v_mul_f32_e32 v60, v210, v106
	v_cndmask_b32_e64 v205, v212, v204, s[100:101]
	v_cndmask_b32_e64 v213, v204, v212, s[100:101]
	v_mul_f32_e32 v61, v211, v107
	v_add_f32_dpp v204, v205, v213 quad_perm:[1,0,3,2] row_mask:0xf bank_mask:0xf bound_ctrl:1
	v_fmac_f32_e32 v58, v108, v182
	v_fmac_f32_e32 v59, v109, v182
	v_add_f32_dpp v204, v204, v204 quad_perm:[2,3,0,1] row_mask:0xf bank_mask:0xf bound_ctrl:1
	v_fmac_f32_e32 v60, v110, v182
	v_fmac_f32_e32 v61, v111, v182
	v_add_f32_dpp v204, v204, v204 row_ror:4 row_mask:0xf bank_mask:0xf bound_ctrl:1
	ds_read_b128 v[84:87], v195 offset:17472
	ds_read_b128 v[88:91], v195 offset:17728
	v_add_f32_dpp v204, v204, v204 row_ror:8 row_mask:0xf bank_mask:0xf bound_ctrl:1
	ds_read_b128 v[92:95], v195 offset:17984
	ds_read_b128 v[96:99], v195 offset:18240
	ds_read_b128 v[100:103], v195 offset:18496
	ds_read_b32 v63, v127 offset:18752
	v_fmac_f32_dpp v58, v204, v196 quad_perm:[1,1,3,3] row_mask:0xf bank_mask:0xf
	v_fmac_f32_dpp v59, v204, v197 quad_perm:[1,1,3,3] row_mask:0xf bank_mask:0xf
	v_fmac_f32_dpp v60, v204, v198 quad_perm:[1,1,3,3] row_mask:0xf bank_mask:0xf
	v_fmac_f32_dpp v61, v204, v199 quad_perm:[1,1,3,3] row_mask:0xf bank_mask:0xf
	v_cndmask_b32_e64 v214, v214, v204, s[68:69]
	s_waitcnt lgkmcnt(6)
	v_mul_f32_e32 v204, v58, v72
	v_mul_f32_e32 v212, v58, v200
	v_fmac_f32_e32 v204, v59, v73
	v_fmac_f32_e32 v212, v59, v201
	v_fmac_f32_e32 v204, v60, v74
	v_fmac_f32_e32 v212, v60, v202
	v_fmac_f32_e32 v204, v61, v75
	v_fmac_f32_e32 v212, v61, v203
	v_mul_f32_e32 v208, v58, v64
	v_mul_f32_e32 v209, v59, v65
	v_mul_f32_e32 v210, v60, v66
	v_cndmask_b32_e64 v205, v204, v212, s[100:101]
	v_cndmask_b32_e64 v213, v212, v204, s[100:101]
	v_mul_f32_e32 v211, v61, v67
	v_add_f32_dpp v204, v205, v213 quad_perm:[1,0,3,2] row_mask:0xf bank_mask:0xf bound_ctrl:1
	v_fmac_f32_e32 v208, v68, v62
	v_fmac_f32_e32 v209, v69, v62
	v_add_f32_dpp v204, v204, v204 quad_perm:[2,3,0,1] row_mask:0xf bank_mask:0xf bound_ctrl:1
	v_fmac_f32_e32 v210, v70, v62
	v_fmac_f32_e32 v211, v71, v62
	v_add_f32_dpp v204, v204, v204 row_ror:4 row_mask:0xf bank_mask:0xf bound_ctrl:1
	ds_read_b128 v[104:107], v195 offset:18816
	ds_read_b128 v[108:111], v195 offset:19072
	v_add_f32_dpp v204, v204, v204 row_ror:8 row_mask:0xf bank_mask:0xf bound_ctrl:1
	ds_read_b128 v[112:115], v195 offset:19328
	ds_read_b128 v[196:199], v195 offset:19584
	ds_read_b128 v[200:203], v195 offset:19840
	ds_read_b32 v182, v127 offset:20096
	v_fmac_f32_dpp v208, v204, v76 quad_perm:[0,0,2,2] row_mask:0xf bank_mask:0xf
	v_fmac_f32_dpp v209, v204, v77 quad_perm:[0,0,2,2] row_mask:0xf bank_mask:0xf
	v_fmac_f32_dpp v210, v204, v78 quad_perm:[0,0,2,2] row_mask:0xf bank_mask:0xf
	v_fmac_f32_dpp v211, v204, v79 quad_perm:[0,0,2,2] row_mask:0xf bank_mask:0xf
	v_cndmask_b32_e64 v214, v214, v204, s[70:71]
	s_waitcnt lgkmcnt(6)
	v_mul_f32_e32 v204, v208, v92
	v_mul_f32_e32 v212, v208, v80
	v_fmac_f32_e32 v204, v209, v93
	v_fmac_f32_e32 v212, v209, v81
	v_fmac_f32_e32 v204, v210, v94
	v_fmac_f32_e32 v212, v210, v82
	v_fmac_f32_e32 v204, v211, v95
	v_fmac_f32_e32 v212, v211, v83
	v_mul_f32_e32 v58, v208, v84
	v_mul_f32_e32 v59, v209, v85
	v_mul_f32_e32 v60, v210, v86
	v_cndmask_b32_e64 v205, v212, v204, s[100:101]
	v_cndmask_b32_e64 v213, v204, v212, s[100:101]
	v_mul_f32_e32 v61, v211, v87
	v_add_f32_dpp v204, v205, v213 quad_perm:[1,0,3,2] row_mask:0xf bank_mask:0xf bound_ctrl:1
	v_fmac_f32_e32 v58, v88, v63
	v_fmac_f32_e32 v59, v89, v63
	v_add_f32_dpp v204, v204, v204 quad_perm:[2,3,0,1] row_mask:0xf bank_mask:0xf bound_ctrl:1
	v_fmac_f32_e32 v60, v90, v63
	v_fmac_f32_e32 v61, v91, v63
	v_add_f32_dpp v204, v204, v204 row_ror:4 row_mask:0xf bank_mask:0xf bound_ctrl:1
	ds_read_b128 v[64:67], v195 offset:20160
	ds_read_b128 v[68:71], v195 offset:20416
	v_add_f32_dpp v204, v204, v204 row_ror:8 row_mask:0xf bank_mask:0xf bound_ctrl:1
	ds_read_b128 v[72:75], v195 offset:20672
	ds_read_b128 v[76:79], v195 offset:20928
	ds_read_b128 v[80:83], v195 offset:21184
	ds_read_b32 v62, v127 offset:21440
	v_fmac_f32_dpp v58, v204, v96 quad_perm:[1,1,3,3] row_mask:0xf bank_mask:0xf
	v_fmac_f32_dpp v59, v204, v97 quad_perm:[1,1,3,3] row_mask:0xf bank_mask:0xf
	v_fmac_f32_dpp v60, v204, v98 quad_perm:[1,1,3,3] row_mask:0xf bank_mask:0xf
	v_fmac_f32_dpp v61, v204, v99 quad_perm:[1,1,3,3] row_mask:0xf bank_mask:0xf
	v_cndmask_b32_e64 v214, v214, v204, s[72:73]
	s_waitcnt lgkmcnt(6)
	v_mul_f32_e32 v204, v58, v112
	v_mul_f32_e32 v212, v58, v100
	v_fmac_f32_e32 v204, v59, v113
	v_fmac_f32_e32 v212, v59, v101
	v_fmac_f32_e32 v204, v60, v114
	v_fmac_f32_e32 v212, v60, v102
	v_fmac_f32_e32 v204, v61, v115
	v_fmac_f32_e32 v212, v61, v103
	v_mul_f32_e32 v208, v58, v104
	v_mul_f32_e32 v209, v59, v105
	v_mul_f32_e32 v210, v60, v106
	v_cndmask_b32_e64 v205, v204, v212, s[100:101]
	v_cndmask_b32_e64 v213, v212, v204, s[100:101]
	v_mul_f32_e32 v211, v61, v107
	v_add_f32_dpp v204, v205, v213 quad_perm:[1,0,3,2] row_mask:0xf bank_mask:0xf bound_ctrl:1
	v_fmac_f32_e32 v208, v108, v182
	v_fmac_f32_e32 v209, v109, v182
	v_add_f32_dpp v204, v204, v204 quad_perm:[2,3,0,1] row_mask:0xf bank_mask:0xf bound_ctrl:1
	v_fmac_f32_e32 v210, v110, v182
	v_fmac_f32_e32 v211, v111, v182
	v_add_f32_dpp v204, v204, v204 row_ror:4 row_mask:0xf bank_mask:0xf bound_ctrl:1
	ds_read_b128 v[84:87], v195 offset:21504
	ds_read_b128 v[88:91], v195 offset:21760
	v_add_f32_dpp v204, v204, v204 row_ror:8 row_mask:0xf bank_mask:0xf bound_ctrl:1
	ds_read_b128 v[92:95], v195 offset:22016
	ds_read_b128 v[96:99], v195 offset:22272
	ds_read_b128 v[100:103], v195 offset:22528
	ds_read_b32 v63, v127 offset:22784
	v_fmac_f32_dpp v208, v204, v196 quad_perm:[0,0,2,2] row_mask:0xf bank_mask:0xf
	v_fmac_f32_dpp v209, v204, v197 quad_perm:[0,0,2,2] row_mask:0xf bank_mask:0xf
	v_fmac_f32_dpp v210, v204, v198 quad_perm:[0,0,2,2] row_mask:0xf bank_mask:0xf
	v_fmac_f32_dpp v211, v204, v199 quad_perm:[0,0,2,2] row_mask:0xf bank_mask:0xf
	v_cndmask_b32_e64 v214, v214, v204, s[74:75]
	s_waitcnt lgkmcnt(6)
; #define LAS __attribute__((address_space(3)))
; template <int CTRL> __device__ __forceinline__ float dppf(float v) { return __int_as_float(__builtin_amdgcn_update_dpp(0, __float_as_int(v), CTRL, 0xf, 0xf, true)); }
; __device__ __forceinline__ void scan_phase(const Args& a, LAS unsigned char* lds, const bf16* Z, const float* W, const bf16* Aa, const bf16* KK, float* Y, int tid, int lane, int wave) {
;     ...
;                 for (int q = 0; q < SCH; ++q) {
;                     const f32x4 wv = pw[q % 3], kv = pk[q % 3], av = pa[q % 3], bv = pb[q % 3], rv = pr[q % 3]; const float vv = pv[q % 3];
;                     if (q + 2 < SCH) {
;                         const LAS float* p = sb + (q + 2) * SROW; const int i = (q + 2) % 3;
;                         pw[i] = *(const LAS f32x4*)p; pk[i] = *(const LAS f32x4*)(p + 64); pa[i] = *(const LAS f32x4*)(p + 128); pb[i] = *(const LAS f32x4*)(p + 192); pr[i] = *(const LAS f32x4*)(p + 256);
;                         pv[i] = vb[(q + 2) * SROW];
;                     }
;                     f32x2 t2 = S01 * (f32x2){av.x, av.y}; t2 = S23 * (f32x2){av.z, av.w} + t2;
;                     float sa = t2.x + t2.y;
;                     sa += dppf<0xB1>(sa); yd += dppf<0xB1>(yd);
;                     sa += dppf<0x4E>(sa); yd += dppf<0x4E>(yd);
;                     sa += dppf<0x141>(sa); yd += dppf<0x141>(yd);
;                     sa += dppf<0x140>(sa); yd += dppf<0x140>(yd);
;                     if (q > 0) { if (q <= 16) ykA = (j == q - 1) ? yd : ykA; else ykB = (j == q - 17) ? yd : ykB; }
;                     const f32x2 u01 = S01 * (f32x2){wv.x, wv.y} + (f32x2){kv.x, kv.y} * vv, u23 = S23 * (f32x2){wv.z, wv.w} + (f32x2){kv.z, kv.w} * vv;
;                     S01 = u01 + (f32x2){bv.x, bv.y} * sa; S23 = u23 + (f32x2){bv.z, bv.w} * sa;
;                     f32x2 y2 = S01 * (f32x2){rv.x, rv.y}; y2 = S23 * (f32x2){rv.z, rv.w} + y2;
;                     yd = y2.x + y2.y;
;                 }
	v_mul_f32_e32 v204, v208, v72
	v_mul_f32_e32 v212, v208, v200
	v_fmac_f32_e32 v204, v209, v73
	v_fmac_f32_e32 v212, v209, v201
	v_fmac_f32_e32 v204, v210, v74
	v_fmac_f32_e32 v212, v210, v202
	v_fmac_f32_e32 v204, v211, v75
	v_fmac_f32_e32 v212, v211, v203
	v_mul_f32_e32 v58, v208, v64
	v_mul_f32_e32 v59, v209, v65
	v_mul_f32_e32 v60, v210, v66
	v_cndmask_b32_e64 v205, v212, v204, s[100:101]
	v_cndmask_b32_e64 v213, v204, v212, s[100:101]
	v_mul_f32_e32 v61, v211, v67
	v_add_f32_dpp v204, v205, v213 quad_perm:[1,0,3,2] row_mask:0xf bank_mask:0xf bound_ctrl:1
	v_fmac_f32_e32 v58, v68, v62
	v_fmac_f32_e32 v59, v69, v62
	v_add_f32_dpp v204, v204, v204 quad_perm:[2,3,0,1] row_mask:0xf bank_mask:0xf bound_ctrl:1
	v_fmac_f32_e32 v60, v70, v62
	v_fmac_f32_e32 v61, v71, v62
	v_add_f32_dpp v204, v204, v204 row_ror:4 row_mask:0xf bank_mask:0xf bound_ctrl:1
	ds_read_b128 v[104:107], v195 offset:22848
	ds_read_b128 v[108:111], v195 offset:23104
	v_add_f32_dpp v204, v204, v204 row_ror:8 row_mask:0xf bank_mask:0xf bound_ctrl:1
	ds_read_b128 v[112:115], v195 offset:23360
	ds_read_b128 v[196:199], v195 offset:23616
	ds_read_b128 v[200:203], v195 offset:23872
	ds_read_b32 v182, v127 offset:24128
	v_fmac_f32_dpp v58, v204, v76 quad_perm:[1,1,3,3] row_mask:0xf bank_mask:0xf
	v_fmac_f32_dpp v59, v204, v77 quad_perm:[1,1,3,3] row_mask:0xf bank_mask:0xf
	v_fmac_f32_dpp v60, v204, v78 quad_perm:[1,1,3,3] row_mask:0xf bank_mask:0xf
	v_fmac_f32_dpp v61, v204, v79 quad_perm:[1,1,3,3] row_mask:0xf bank_mask:0xf
	v_cndmask_b32_e64 v214, v214, v204, s[76:77]
	s_waitcnt lgkmcnt(6)
	v_mul_f32_e32 v204, v58, v92
	v_mul_f32_e32 v212, v58, v80
	v_fmac_f32_e32 v204, v59, v93
	v_fmac_f32_e32 v212, v59, v81
	v_fmac_f32_e32 v204, v60, v94
	v_fmac_f32_e32 v212, v60, v82
	v_fmac_f32_e32 v204, v61, v95
	v_fmac_f32_e32 v212, v61, v83
	v_mul_f32_e32 v208, v58, v84
	v_mul_f32_e32 v209, v59, v85
	v_mul_f32_e32 v210, v60, v86
	v_cndmask_b32_e64 v205, v204, v212, s[100:101]
	v_cndmask_b32_e64 v213, v212, v204, s[100:101]
	v_mul_f32_e32 v211, v61, v87
	v_add_f32_dpp v204, v205, v213 quad_perm:[1,0,3,2] row_mask:0xf bank_mask:0xf bound_ctrl:1
	v_fmac_f32_e32 v208, v88, v63
	v_fmac_f32_e32 v209, v89, v63
	v_add_f32_dpp v204, v204, v204 quad_perm:[2,3,0,1] row_mask:0xf bank_mask:0xf bound_ctrl:1
	v_fmac_f32_e32 v210, v90, v63
	v_fmac_f32_e32 v211, v91, v63
	v_add_f32_dpp v204, v204, v204 row_ror:4 row_mask:0xf bank_mask:0xf bound_ctrl:1
	ds_read_b128 v[64:67], v195 offset:24192
	ds_read_b128 v[68:71], v195 offset:24448
	v_add_f32_dpp v204, v204, v204 row_ror:8 row_mask:0xf bank_mask:0xf bound_ctrl:1
	ds_read_b128 v[72:75], v195 offset:24704
	ds_read_b128 v[76:79], v195 offset:24960
	ds_read_b128 v[80:83], v195 offset:25216
	ds_read_b32 v62, v127 offset:25472
	v_fmac_f32_dpp v208, v204, v96 quad_perm:[0,0,2,2] row_mask:0xf bank_mask:0xf
	v_fmac_f32_dpp v209, v204, v97 quad_perm:[0,0,2,2] row_mask:0xf bank_mask:0xf
	v_fmac_f32_dpp v210, v204, v98 quad_perm:[0,0,2,2] row_mask:0xf bank_mask:0xf
	v_fmac_f32_dpp v211, v204, v99 quad_perm:[0,0,2,2] row_mask:0xf bank_mask:0xf
	v_cndmask_b32_e64 v214, v214, v204, s[96:97]
	s_waitcnt lgkmcnt(6)
	v_mul_f32_e32 v204, v208, v112
	v_mul_f32_e32 v212, v208, v100
	v_fmac_f32_e32 v204, v209, v113
	v_fmac_f32_e32 v212, v209, v101
	v_fmac_f32_e32 v204, v210, v114
	v_fmac_f32_e32 v212, v210, v102
	v_fmac_f32_e32 v204, v211, v115
	v_fmac_f32_e32 v212, v211, v103
	v_mul_f32_e32 v58, v208, v104
	v_mul_f32_e32 v59, v209, v105
	v_mul_f32_e32 v60, v210, v106
	v_cndmask_b32_e64 v205, v212, v204, s[100:101]
	v_cndmask_b32_e64 v213, v204, v212, s[100:101]
	v_mul_f32_e32 v61, v211, v107
	v_add_f32_dpp v204, v205, v213 quad_perm:[1,0,3,2] row_mask:0xf bank_mask:0xf bound_ctrl:1
	v_fmac_f32_e32 v58, v108, v182
	v_fmac_f32_e32 v59, v109, v182
	v_add_f32_dpp v204, v204, v204 quad_perm:[2,3,0,1] row_mask:0xf bank_mask:0xf bound_ctrl:1
	v_fmac_f32_e32 v60, v110, v182
	v_fmac_f32_e32 v61, v111, v182
	v_add_f32_dpp v204, v204, v204 row_ror:4 row_mask:0xf bank_mask:0xf bound_ctrl:1
	ds_read_b128 v[84:87], v195 offset:25536
	ds_read_b128 v[88:91], v195 offset:25792
	v_add_f32_dpp v204, v204, v204 row_ror:8 row_mask:0xf bank_mask:0xf bound_ctrl:1
	ds_read_b128 v[92:95], v195 offset:26048
	ds_read_b128 v[96:99], v195 offset:26304
	ds_read_b128 v[100:103], v195 offset:26560
	ds_read_b32 v63, v127 offset:26816
	v_fmac_f32_dpp v58, v204, v196 quad_perm:[1,1,3,3] row_mask:0xf bank_mask:0xf
	v_fmac_f32_dpp v59, v204, v197 quad_perm:[1,1,3,3] row_mask:0xf bank_mask:0xf
	v_fmac_f32_dpp v60, v204, v198 quad_perm:[1,1,3,3] row_mask:0xf bank_mask:0xf
	v_fmac_f32_dpp v61, v204, v199 quad_perm:[1,1,3,3] row_mask:0xf bank_mask:0xf
	v_cndmask_b32_e64 v215, 0, v204, s[82:83]
	s_waitcnt lgkmcnt(6)
	v_mul_f32_e32 v204, v58, v72
	v_mul_f32_e32 v212, v58, v200
	v_fmac_f32_e32 v204, v59, v73
	v_fmac_f32_e32 v212, v59, v201
	v_fmac_f32_e32 v204, v60, v74
	v_fmac_f32_e32 v212, v60, v202
	v_fmac_f32_e32 v204, v61, v75
	v_fmac_f32_e32 v212, v61, v203
	v_mul_f32_e32 v208, v58, v64
	v_mul_f32_e32 v209, v59, v65
	v_mul_f32_e32 v210, v60, v66
	v_cndmask_b32_e64 v205, v204, v212, s[100:101]
	v_cndmask_b32_e64 v213, v212, v204, s[100:101]
	v_mul_f32_e32 v211, v61, v67
	v_add_f32_dpp v204, v205, v213 quad_perm:[1,0,3,2] row_mask:0xf bank_mask:0xf bound_ctrl:1
	v_fmac_f32_e32 v208, v68, v62
	v_fmac_f32_e32 v209, v69, v62
	v_add_f32_dpp v204, v204, v204 quad_perm:[2,3,0,1] row_mask:0xf bank_mask:0xf bound_ctrl:1
	v_fmac_f32_e32 v210, v70, v62
	v_fmac_f32_e32 v211, v71, v62
	v_add_f32_dpp v204, v204, v204 row_ror:4 row_mask:0xf bank_mask:0xf bound_ctrl:1
	ds_read_b128 v[104:107], v195 offset:26880
	ds_read_b128 v[108:111], v195 offset:27136
	v_add_f32_dpp v204, v204, v204 row_ror:8 row_mask:0xf bank_mask:0xf bound_ctrl:1
	ds_read_b128 v[112:115], v195 offset:27392
	ds_read_b128 v[196:199], v195 offset:27648
	ds_read_b128 v[200:203], v195 offset:27904
	ds_read_b32 v182, v127 offset:28160
	v_fmac_f32_dpp v208, v204, v76 quad_perm:[0,0,2,2] row_mask:0xf bank_mask:0xf
	v_fmac_f32_dpp v209, v204, v77 quad_perm:[0,0,2,2] row_mask:0xf bank_mask:0xf
	v_fmac_f32_dpp v210, v204, v78 quad_perm:[0,0,2,2] row_mask:0xf bank_mask:0xf
	v_fmac_f32_dpp v211, v204, v79 quad_perm:[0,0,2,2] row_mask:0xf bank_mask:0xf
	v_cndmask_b32_e64 v215, v215, v204, s[80:81]
	s_waitcnt lgkmcnt(6)
; #define LAS __attribute__((address_space(3)))
; template <int CTRL> __device__ __forceinline__ float dppf(float v) { return __int_as_float(__builtin_amdgcn_update_dpp(0, __float_as_int(v), CTRL, 0xf, 0xf, true)); }
; __device__ __forceinline__ void scan_phase(const Args& a, LAS unsigned char* lds, const bf16* Z, const float* W, const bf16* Aa, const bf16* KK, float* Y, int tid, int lane, int wave) {
;     ...
;                 for (int q = 0; q < SCH; ++q) {
;                     const f32x4 wv = pw[q % 3], kv = pk[q % 3], av = pa[q % 3], bv = pb[q % 3], rv = pr[q % 3]; const float vv = pv[q % 3];
;                     if (q + 2 < SCH) {
;                         const LAS float* p = sb + (q + 2) * SROW; const int i = (q + 2) % 3;
;                         pw[i] = *(const LAS f32x4*)p; pk[i] = *(const LAS f32x4*)(p + 64); pa[i] = *(const LAS f32x4*)(p + 128); pb[i] = *(const LAS f32x4*)(p + 192); pr[i] = *(const LAS f32x4*)(p + 256);
;                         pv[i] = vb[(q + 2) * SROW];
;                     }
;                     f32x2 t2 = S01 * (f32x2){av.x, av.y}; t2 = S23 * (f32x2){av.z, av.w} + t2;
;                     float sa = t2.x + t2.y;
;                     sa += dppf<0xB1>(sa); yd += dppf<0xB1>(yd);
;                     sa += dppf<0x4E>(sa); yd += dppf<0x4E>(yd);
;                     sa += dppf<0x141>(sa); yd += dppf<0x141>(yd);
;                     sa += dppf<0x140>(sa); yd += dppf<0x140>(yd);
;                     if (q > 0) { if (q <= 16) ykA = (j == q - 1) ? yd : ykA; else ykB = (j == q - 17) ? yd : ykB; }
;                     const f32x2 u01 = S01 * (f32x2){wv.x, wv.y} + (f32x2){kv.x, kv.y} * vv, u23 = S23 * (f32x2){wv.z, wv.w} + (f32x2){kv.z, kv.w} * vv;
;                     S01 = u01 + (f32x2){bv.x, bv.y} * sa; S23 = u23 + (f32x2){bv.z, bv.w} * sa;
;                     f32x2 y2 = S01 * (f32x2){rv.x, rv.y}; y2 = S23 * (f32x2){rv.z, rv.w} + y2;
;                     yd = y2.x + y2.y;
;                 }
	v_mul_f32_e32 v204, v208, v92
	v_mul_f32_e32 v212, v208, v80
	v_fmac_f32_e32 v204, v209, v93
	v_fmac_f32_e32 v212, v209, v81
	v_fmac_f32_e32 v204, v210, v94
	v_fmac_f32_e32 v212, v210, v82
	v_fmac_f32_e32 v204, v211, v95
	v_fmac_f32_e32 v212, v211, v83
	v_mul_f32_e32 v58, v208, v84
	v_mul_f32_e32 v59, v209, v85
	v_mul_f32_e32 v60, v210, v86
	v_cndmask_b32_e64 v205, v212, v204, s[100:101]
	v_cndmask_b32_e64 v213, v204, v212, s[100:101]
	v_mul_f32_e32 v61, v211, v87
	v_add_f32_dpp v204, v205, v213 quad_perm:[1,0,3,2] row_mask:0xf bank_mask:0xf bound_ctrl:1
	v_fmac_f32_e32 v58, v88, v63
	v_fmac_f32_e32 v59, v89, v63
	v_add_f32_dpp v204, v204, v204 quad_perm:[2,3,0,1] row_mask:0xf bank_mask:0xf bound_ctrl:1
	v_fmac_f32_e32 v60, v90, v63
	v_fmac_f32_e32 v61, v91, v63
	v_add_f32_dpp v204, v204, v204 row_ror:4 row_mask:0xf bank_mask:0xf bound_ctrl:1
	ds_read_b128 v[64:67], v195 offset:28224
	ds_read_b128 v[68:71], v195 offset:28480
	v_add_f32_dpp v204, v204, v204 row_ror:8 row_mask:0xf bank_mask:0xf bound_ctrl:1
	ds_read_b128 v[72:75], v195 offset:28736
	ds_read_b128 v[76:79], v195 offset:28992
	ds_read_b128 v[80:83], v195 offset:29248
	ds_read_b32 v62, v127 offset:29504
	v_fmac_f32_dpp v58, v204, v96 quad_perm:[1,1,3,3] row_mask:0xf bank_mask:0xf
	v_fmac_f32_dpp v59, v204, v97 quad_perm:[1,1,3,3] row_mask:0xf bank_mask:0xf
	v_fmac_f32_dpp v60, v204, v98 quad_perm:[1,1,3,3] row_mask:0xf bank_mask:0xf
	v_fmac_f32_dpp v61, v204, v99 quad_perm:[1,1,3,3] row_mask:0xf bank_mask:0xf
	v_cndmask_b32_e64 v215, v215, v204, s[6:7]
	s_waitcnt lgkmcnt(6)
	v_mul_f32_e32 v204, v58, v112
	v_mul_f32_e32 v212, v58, v100
	v_fmac_f32_e32 v204, v59, v113
	v_fmac_f32_e32 v212, v59, v101
	v_fmac_f32_e32 v204, v60, v114
	v_fmac_f32_e32 v212, v60, v102
	v_fmac_f32_e32 v204, v61, v115
	v_fmac_f32_e32 v212, v61, v103
	v_mul_f32_e32 v208, v58, v104
	v_mul_f32_e32 v209, v59, v105
	v_mul_f32_e32 v210, v60, v106
	v_cndmask_b32_e64 v205, v204, v212, s[100:101]
	v_cndmask_b32_e64 v213, v212, v204, s[100:101]
	v_mul_f32_e32 v211, v61, v107
	v_add_f32_dpp v204, v205, v213 quad_perm:[1,0,3,2] row_mask:0xf bank_mask:0xf bound_ctrl:1
	v_fmac_f32_e32 v208, v108, v182
	v_fmac_f32_e32 v209, v109, v182
	v_add_f32_dpp v204, v204, v204 quad_perm:[2,3,0,1] row_mask:0xf bank_mask:0xf bound_ctrl:1
	v_fmac_f32_e32 v210, v110, v182
	v_fmac_f32_e32 v211, v111, v182
	v_add_f32_dpp v204, v204, v204 row_ror:4 row_mask:0xf bank_mask:0xf bound_ctrl:1
	ds_read_b128 v[84:87], v195 offset:29568
	ds_read_b128 v[88:91], v195 offset:29824
	v_add_f32_dpp v204, v204, v204 row_ror:8 row_mask:0xf bank_mask:0xf bound_ctrl:1
	ds_read_b128 v[92:95], v195 offset:30080
	ds_read_b128 v[96:99], v195 offset:30336
	ds_read_b128 v[100:103], v195 offset:30592
	ds_read_b32 v63, v127 offset:30848
	v_fmac_f32_dpp v208, v204, v196 quad_perm:[0,0,2,2] row_mask:0xf bank_mask:0xf
	v_fmac_f32_dpp v209, v204, v197 quad_perm:[0,0,2,2] row_mask:0xf bank_mask:0xf
	v_fmac_f32_dpp v210, v204, v198 quad_perm:[0,0,2,2] row_mask:0xf bank_mask:0xf
	v_fmac_f32_dpp v211, v204, v199 quad_perm:[0,0,2,2] row_mask:0xf bank_mask:0xf
	v_cndmask_b32_e64 v215, v215, v204, s[8:9]
	s_waitcnt lgkmcnt(6)
	v_mul_f32_e32 v204, v208, v72
	v_mul_f32_e32 v212, v208, v200
	v_fmac_f32_e32 v204, v209, v73
	v_fmac_f32_e32 v212, v209, v201
	v_fmac_f32_e32 v204, v210, v74
	v_fmac_f32_e32 v212, v210, v202
	v_fmac_f32_e32 v204, v211, v75
	v_fmac_f32_e32 v212, v211, v203
	v_mul_f32_e32 v58, v208, v64
	v_mul_f32_e32 v59, v209, v65
	v_mul_f32_e32 v60, v210, v66
	v_cndmask_b32_e64 v205, v212, v204, s[100:101]
	v_cndmask_b32_e64 v213, v204, v212, s[100:101]
	v_mul_f32_e32 v61, v211, v67
	v_add_f32_dpp v204, v205, v213 quad_perm:[1,0,3,2] row_mask:0xf bank_mask:0xf bound_ctrl:1
	v_fmac_f32_e32 v58, v68, v62
	v_fmac_f32_e32 v59, v69, v62
	v_add_f32_dpp v204, v204, v204 quad_perm:[2,3,0,1] row_mask:0xf bank_mask:0xf bound_ctrl:1
	v_fmac_f32_e32 v60, v70, v62
	v_fmac_f32_e32 v61, v71, v62
	v_add_f32_dpp v204, v204, v204 row_ror:4 row_mask:0xf bank_mask:0xf bound_ctrl:1
	ds_read_b128 v[104:107], v195 offset:30912
	ds_read_b128 v[108:111], v195 offset:31168
	v_add_f32_dpp v204, v204, v204 row_ror:8 row_mask:0xf bank_mask:0xf bound_ctrl:1
	ds_read_b128 v[112:115], v195 offset:31424
	ds_read_b128 v[196:199], v195 offset:31680
	ds_read_b128 v[200:203], v195 offset:31936
	ds_read_b32 v182, v127 offset:32192
	v_fmac_f32_dpp v58, v204, v76 quad_perm:[1,1,3,3] row_mask:0xf bank_mask:0xf
	v_fmac_f32_dpp v59, v204, v77 quad_perm:[1,1,3,3] row_mask:0xf bank_mask:0xf
	v_fmac_f32_dpp v60, v204, v78 quad_perm:[1,1,3,3] row_mask:0xf bank_mask:0xf
	v_fmac_f32_dpp v61, v204, v79 quad_perm:[1,1,3,3] row_mask:0xf bank_mask:0xf
	v_cndmask_b32_e64 v215, v215, v204, s[10:11]
	s_waitcnt lgkmcnt(6)
	v_mul_f32_e32 v204, v58, v92
	v_mul_f32_e32 v212, v58, v80
	v_fmac_f32_e32 v204, v59, v93
	v_fmac_f32_e32 v212, v59, v81
	v_fmac_f32_e32 v204, v60, v94
	v_fmac_f32_e32 v212, v60, v82
	v_fmac_f32_e32 v204, v61, v95
	v_fmac_f32_e32 v212, v61, v83
	v_mul_f32_e32 v208, v58, v84
	v_mul_f32_e32 v209, v59, v85
	v_mul_f32_e32 v210, v60, v86
	v_cndmask_b32_e64 v205, v204, v212, s[100:101]
	v_cndmask_b32_e64 v213, v212, v204, s[100:101]
	v_mul_f32_e32 v211, v61, v87
	v_add_f32_dpp v204, v205, v213 quad_perm:[1,0,3,2] row_mask:0xf bank_mask:0xf bound_ctrl:1
	v_fmac_f32_e32 v208, v88, v63
	v_fmac_f32_e32 v209, v89, v63
	v_add_f32_dpp v204, v204, v204 quad_perm:[2,3,0,1] row_mask:0xf bank_mask:0xf bound_ctrl:1
	v_fmac_f32_e32 v210, v90, v63
	v_fmac_f32_e32 v211, v91, v63
	v_add_f32_dpp v204, v204, v204 row_ror:4 row_mask:0xf bank_mask:0xf bound_ctrl:1
	ds_read_b128 v[64:67], v195 offset:32256
	ds_read_b128 v[68:71], v195 offset:32512
	v_add_f32_dpp v204, v204, v204 row_ror:8 row_mask:0xf bank_mask:0xf bound_ctrl:1
	ds_read_b128 v[72:75], v195 offset:32768
	ds_read_b128 v[76:79], v195 offset:33024
	ds_read_b128 v[80:83], v195 offset:33280
	ds_read_b32 v62, v127 offset:33536
	v_fmac_f32_dpp v208, v204, v96 quad_perm:[0,0,2,2] row_mask:0xf bank_mask:0xf
	v_fmac_f32_dpp v209, v204, v97 quad_perm:[0,0,2,2] row_mask:0xf bank_mask:0xf
	v_fmac_f32_dpp v210, v204, v98 quad_perm:[0,0,2,2] row_mask:0xf bank_mask:0xf
	v_fmac_f32_dpp v211, v204, v99 quad_perm:[0,0,2,2] row_mask:0xf bank_mask:0xf
	v_cndmask_b32_e64 v215, v215, v204, s[90:91]
	s_waitcnt lgkmcnt(6)
; #define LAS __attribute__((address_space(3)))
; template <int CTRL> __device__ __forceinline__ float dppf(float v) { return __int_as_float(__builtin_amdgcn_update_dpp(0, __float_as_int(v), CTRL, 0xf, 0xf, true)); }
; __device__ __forceinline__ void scan_phase(const Args& a, LAS unsigned char* lds, const bf16* Z, const float* W, const bf16* Aa, const bf16* KK, float* Y, int tid, int lane, int wave) {
;     ...
;                 for (int q = 0; q < SCH; ++q) {
;                     const f32x4 wv = pw[q % 3], kv = pk[q % 3], av = pa[q % 3], bv = pb[q % 3], rv = pr[q % 3]; const float vv = pv[q % 3];
;                     if (q + 2 < SCH) {
;                         const LAS float* p = sb + (q + 2) * SROW; const int i = (q + 2) % 3;
;                         pw[i] = *(const LAS f32x4*)p; pk[i] = *(const LAS f32x4*)(p + 64); pa[i] = *(const LAS f32x4*)(p + 128); pb[i] = *(const LAS f32x4*)(p + 192); pr[i] = *(const LAS f32x4*)(p + 256);
;                         pv[i] = vb[(q + 2) * SROW];
;                     }
;                     f32x2 t2 = S01 * (f32x2){av.x, av.y}; t2 = S23 * (f32x2){av.z, av.w} + t2;
;                     float sa = t2.x + t2.y;
;                     sa += dppf<0xB1>(sa); yd += dppf<0xB1>(yd);
;                     sa += dppf<0x4E>(sa); yd += dppf<0x4E>(yd);
;                     sa += dppf<0x141>(sa); yd += dppf<0x141>(yd);
;                     sa += dppf<0x140>(sa); yd += dppf<0x140>(yd);
;                     if (q > 0) { if (q <= 16) ykA = (j == q - 1) ? yd : ykA; else ykB = (j == q - 17) ? yd : ykB; }
;                     const f32x2 u01 = S01 * (f32x2){wv.x, wv.y} + (f32x2){kv.x, kv.y} * vv, u23 = S23 * (f32x2){wv.z, wv.w} + (f32x2){kv.z, kv.w} * vv;
;                     S01 = u01 + (f32x2){bv.x, bv.y} * sa; S23 = u23 + (f32x2){bv.z, bv.w} * sa;
;                     f32x2 y2 = S01 * (f32x2){rv.x, rv.y}; y2 = S23 * (f32x2){rv.z, rv.w} + y2;
;                     yd = y2.x + y2.y;
;                 }
	v_mul_f32_e32 v204, v208, v112
	v_mul_f32_e32 v212, v208, v100
	v_fmac_f32_e32 v204, v209, v113
	v_fmac_f32_e32 v212, v209, v101
	v_fmac_f32_e32 v204, v210, v114
	v_fmac_f32_e32 v212, v210, v102
	v_fmac_f32_e32 v204, v211, v115
	v_fmac_f32_e32 v212, v211, v103
	v_mul_f32_e32 v58, v208, v104
	v_mul_f32_e32 v59, v209, v105
	v_mul_f32_e32 v60, v210, v106
	v_cndmask_b32_e64 v205, v212, v204, s[100:101]
	v_cndmask_b32_e64 v213, v204, v212, s[100:101]
	v_mul_f32_e32 v61, v211, v107
	v_add_f32_dpp v204, v205, v213 quad_perm:[1,0,3,2] row_mask:0xf bank_mask:0xf bound_ctrl:1
	v_fmac_f32_e32 v58, v108, v182
	v_fmac_f32_e32 v59, v109, v182
	v_add_f32_dpp v204, v204, v204 quad_perm:[2,3,0,1] row_mask:0xf bank_mask:0xf bound_ctrl:1
	v_fmac_f32_e32 v60, v110, v182
	v_fmac_f32_e32 v61, v111, v182
	v_add_f32_dpp v204, v204, v204 row_ror:4 row_mask:0xf bank_mask:0xf bound_ctrl:1
	ds_read_b128 v[84:87], v195 offset:33600
	ds_read_b128 v[88:91], v195 offset:33856
	v_add_f32_dpp v204, v204, v204 row_ror:8 row_mask:0xf bank_mask:0xf bound_ctrl:1
	ds_read_b128 v[92:95], v195 offset:34112
	ds_read_b128 v[96:99], v195 offset:34368
	ds_read_b128 v[100:103], v195 offset:34624
	ds_read_b32 v63, v127 offset:34880
	v_fmac_f32_dpp v58, v204, v196 quad_perm:[1,1,3,3] row_mask:0xf bank_mask:0xf
	v_fmac_f32_dpp v59, v204, v197 quad_perm:[1,1,3,3] row_mask:0xf bank_mask:0xf
	v_fmac_f32_dpp v60, v204, v198 quad_perm:[1,1,3,3] row_mask:0xf bank_mask:0xf
	v_fmac_f32_dpp v61, v204, v199 quad_perm:[1,1,3,3] row_mask:0xf bank_mask:0xf
	v_cndmask_b32_e64 v215, v215, v204, s[60:61]
	s_waitcnt lgkmcnt(6)
	v_mul_f32_e32 v204, v58, v72
	v_mul_f32_e32 v212, v58, v200
	v_fmac_f32_e32 v204, v59, v73
	v_fmac_f32_e32 v212, v59, v201
	v_fmac_f32_e32 v204, v60, v74
	v_fmac_f32_e32 v212, v60, v202
	v_fmac_f32_e32 v204, v61, v75
	v_fmac_f32_e32 v212, v61, v203
	v_mul_f32_e32 v208, v58, v64
	v_mul_f32_e32 v209, v59, v65
	v_mul_f32_e32 v210, v60, v66
	v_cndmask_b32_e64 v205, v204, v212, s[100:101]
	v_cndmask_b32_e64 v213, v212, v204, s[100:101]
	v_mul_f32_e32 v211, v61, v67
	v_add_f32_dpp v204, v205, v213 quad_perm:[1,0,3,2] row_mask:0xf bank_mask:0xf bound_ctrl:1
	v_fmac_f32_e32 v208, v68, v62
	v_fmac_f32_e32 v209, v69, v62
	v_add_f32_dpp v204, v204, v204 quad_perm:[2,3,0,1] row_mask:0xf bank_mask:0xf bound_ctrl:1
	v_fmac_f32_e32 v210, v70, v62
	v_fmac_f32_e32 v211, v71, v62
	v_add_f32_dpp v204, v204, v204 row_ror:4 row_mask:0xf bank_mask:0xf bound_ctrl:1
	ds_read_b128 v[104:107], v195 offset:34944
	ds_read_b128 v[108:111], v195 offset:35200
	v_add_f32_dpp v204, v204, v204 row_ror:8 row_mask:0xf bank_mask:0xf bound_ctrl:1
	ds_read_b128 v[112:115], v195 offset:35456
	ds_read_b128 v[196:199], v195 offset:35712
	ds_read_b128 v[200:203], v195 offset:35968
	ds_read_b32 v182, v127 offset:36224
	v_fmac_f32_dpp v208, v204, v76 quad_perm:[0,0,2,2] row_mask:0xf bank_mask:0xf
	v_fmac_f32_dpp v209, v204, v77 quad_perm:[0,0,2,2] row_mask:0xf bank_mask:0xf
	v_fmac_f32_dpp v210, v204, v78 quad_perm:[0,0,2,2] row_mask:0xf bank_mask:0xf
	v_fmac_f32_dpp v211, v204, v79 quad_perm:[0,0,2,2] row_mask:0xf bank_mask:0xf
	v_cndmask_b32_e64 v215, v215, v204, s[62:63]
	s_waitcnt lgkmcnt(6)
	v_mul_f32_e32 v204, v208, v92
	v_mul_f32_e32 v212, v208, v80
	v_fmac_f32_e32 v204, v209, v93
	v_fmac_f32_e32 v212, v209, v81
	v_fmac_f32_e32 v204, v210, v94
	v_fmac_f32_e32 v212, v210, v82
	v_fmac_f32_e32 v204, v211, v95
	v_fmac_f32_e32 v212, v211, v83
	v_mul_f32_e32 v58, v208, v84
	v_mul_f32_e32 v59, v209, v85
	v_mul_f32_e32 v60, v210, v86
	v_cndmask_b32_e64 v205, v212, v204, s[100:101]
	v_cndmask_b32_e64 v213, v204, v212, s[100:101]
	v_mul_f32_e32 v61, v211, v87
	v_add_f32_dpp v204, v205, v213 quad_perm:[1,0,3,2] row_mask:0xf bank_mask:0xf bound_ctrl:1
	v_fmac_f32_e32 v58, v88, v63
	v_fmac_f32_e32 v59, v89, v63
	v_add_f32_dpp v204, v204, v204 quad_perm:[2,3,0,1] row_mask:0xf bank_mask:0xf bound_ctrl:1
	v_fmac_f32_e32 v60, v90, v63
	v_fmac_f32_e32 v61, v91, v63
	v_add_f32_dpp v204, v204, v204 row_ror:4 row_mask:0xf bank_mask:0xf bound_ctrl:1
	ds_read_b128 v[64:67], v195 offset:36288
	ds_read_b128 v[68:71], v195 offset:36544
	v_add_f32_dpp v204, v204, v204 row_ror:8 row_mask:0xf bank_mask:0xf bound_ctrl:1
	ds_read_b128 v[72:75], v195 offset:36800
	ds_read_b128 v[76:79], v195 offset:37056
	ds_read_b128 v[80:83], v195 offset:37312
	ds_read_b32 v62, v127 offset:37568
	v_fmac_f32_dpp v58, v204, v96 quad_perm:[1,1,3,3] row_mask:0xf bank_mask:0xf
	v_fmac_f32_dpp v59, v204, v97 quad_perm:[1,1,3,3] row_mask:0xf bank_mask:0xf
	v_fmac_f32_dpp v60, v204, v98 quad_perm:[1,1,3,3] row_mask:0xf bank_mask:0xf
	v_fmac_f32_dpp v61, v204, v99 quad_perm:[1,1,3,3] row_mask:0xf bank_mask:0xf
	v_cndmask_b32_e64 v215, v215, v204, s[64:65]
	s_waitcnt lgkmcnt(6)
	v_mul_f32_e32 v204, v58, v112
	v_mul_f32_e32 v212, v58, v100
	v_fmac_f32_e32 v204, v59, v113
	v_fmac_f32_e32 v212, v59, v101
	v_fmac_f32_e32 v204, v60, v114
	v_fmac_f32_e32 v212, v60, v102
	v_fmac_f32_e32 v204, v61, v115
	v_fmac_f32_e32 v212, v61, v103
	v_mul_f32_e32 v208, v58, v104
	v_mul_f32_e32 v209, v59, v105
	v_mul_f32_e32 v210, v60, v106
	v_cndmask_b32_e64 v205, v204, v212, s[100:101]
	v_cndmask_b32_e64 v213, v212, v204, s[100:101]
	v_mul_f32_e32 v211, v61, v107
	v_add_f32_dpp v204, v205, v213 quad_perm:[1,0,3,2] row_mask:0xf bank_mask:0xf bound_ctrl:1
	v_fmac_f32_e32 v208, v108, v182
	v_fmac_f32_e32 v209, v109, v182
	v_add_f32_dpp v204, v204, v204 quad_perm:[2,3,0,1] row_mask:0xf bank_mask:0xf bound_ctrl:1
	v_fmac_f32_e32 v210, v110, v182
	v_fmac_f32_e32 v211, v111, v182
	v_add_f32_dpp v204, v204, v204 row_ror:4 row_mask:0xf bank_mask:0xf bound_ctrl:1
	ds_read_b128 v[84:87], v195 offset:37632
	ds_read_b128 v[88:91], v195 offset:37888
	v_add_f32_dpp v204, v204, v204 row_ror:8 row_mask:0xf bank_mask:0xf bound_ctrl:1
	ds_read_b128 v[92:95], v195 offset:38144
	ds_read_b128 v[96:99], v195 offset:38400
	ds_read_b128 v[100:103], v195 offset:38656
	ds_read_b32 v63, v127 offset:38912
	v_fmac_f32_dpp v208, v204, v196 quad_perm:[0,0,2,2] row_mask:0xf bank_mask:0xf
	v_fmac_f32_dpp v209, v204, v197 quad_perm:[0,0,2,2] row_mask:0xf bank_mask:0xf
	v_fmac_f32_dpp v210, v204, v198 quad_perm:[0,0,2,2] row_mask:0xf bank_mask:0xf
	v_fmac_f32_dpp v211, v204, v199 quad_perm:[0,0,2,2] row_mask:0xf bank_mask:0xf
	v_cndmask_b32_e64 v215, v215, v204, s[66:67]
	s_waitcnt lgkmcnt(6)
; #define LAS __attribute__((address_space(3)))
; template <int CTRL> __device__ __forceinline__ float dppf(float v) { return __int_as_float(__builtin_amdgcn_update_dpp(0, __float_as_int(v), CTRL, 0xf, 0xf, true)); }
; __device__ __forceinline__ void scan_phase(const Args& a, LAS unsigned char* lds, const bf16* Z, const float* W, const bf16* Aa, const bf16* KK, float* Y, int tid, int lane, int wave) {
;     ...
;                 for (int q = 0; q < SCH; ++q) {
;                     const f32x4 wv = pw[q % 3], kv = pk[q % 3], av = pa[q % 3], bv = pb[q % 3], rv = pr[q % 3]; const float vv = pv[q % 3];
;                     if (q + 2 < SCH) {
;                         const LAS float* p = sb + (q + 2) * SROW; const int i = (q + 2) % 3;
;                         pw[i] = *(const LAS f32x4*)p; pk[i] = *(const LAS f32x4*)(p + 64); pa[i] = *(const LAS f32x4*)(p + 128); pb[i] = *(const LAS f32x4*)(p + 192); pr[i] = *(const LAS f32x4*)(p + 256);
;                         pv[i] = vb[(q + 2) * SROW];
;                     }
;                     f32x2 t2 = S01 * (f32x2){av.x, av.y}; t2 = S23 * (f32x2){av.z, av.w} + t2;
;                     float sa = t2.x + t2.y;
;                     sa += dppf<0xB1>(sa); yd += dppf<0xB1>(yd);
;                     sa += dppf<0x4E>(sa); yd += dppf<0x4E>(yd);
;                     sa += dppf<0x141>(sa); yd += dppf<0x141>(yd);
;                     sa += dppf<0x140>(sa); yd += dppf<0x140>(yd);
;                     if (q > 0) { if (q <= 16) ykA = (j == q - 1) ? yd : ykA; else ykB = (j == q - 17) ? yd : ykB; }
;                     const f32x2 u01 = S01 * (f32x2){wv.x, wv.y} + (f32x2){kv.x, kv.y} * vv, u23 = S23 * (f32x2){wv.z, wv.w} + (f32x2){kv.z, kv.w} * vv;
;                     S01 = u01 + (f32x2){bv.x, bv.y} * sa; S23 = u23 + (f32x2){bv.z, bv.w} * sa;
;                     f32x2 y2 = S01 * (f32x2){rv.x, rv.y}; y2 = S23 * (f32x2){rv.z, rv.w} + y2;
;                     yd = y2.x + y2.y;
;                 }
	v_mul_f32_e32 v204, v208, v72
	v_mul_f32_e32 v212, v208, v200
	v_fmac_f32_e32 v204, v209, v73
	v_fmac_f32_e32 v212, v209, v201
	v_fmac_f32_e32 v204, v210, v74
	v_fmac_f32_e32 v212, v210, v202
	v_fmac_f32_e32 v204, v211, v75
	v_fmac_f32_e32 v212, v211, v203
	v_mul_f32_e32 v58, v208, v64
	v_mul_f32_e32 v59, v209, v65
	v_mul_f32_e32 v60, v210, v66
	v_cndmask_b32_e64 v205, v212, v204, s[100:101]
	v_cndmask_b32_e64 v213, v204, v212, s[100:101]
	v_mul_f32_e32 v61, v211, v67
	v_add_f32_dpp v204, v205, v213 quad_perm:[1,0,3,2] row_mask:0xf bank_mask:0xf bound_ctrl:1
	v_fmac_f32_e32 v58, v68, v62
	v_fmac_f32_e32 v59, v69, v62
	v_add_f32_dpp v204, v204, v204 quad_perm:[2,3,0,1] row_mask:0xf bank_mask:0xf bound_ctrl:1
	v_fmac_f32_e32 v60, v70, v62
	v_fmac_f32_e32 v61, v71, v62
	v_add_f32_dpp v204, v204, v204 row_ror:4 row_mask:0xf bank_mask:0xf bound_ctrl:1
	ds_read_b128 v[104:107], v195 offset:38976
	ds_read_b128 v[108:111], v195 offset:39232
	v_add_f32_dpp v204, v204, v204 row_ror:8 row_mask:0xf bank_mask:0xf bound_ctrl:1
	ds_read_b128 v[112:115], v195 offset:39488
	ds_read_b128 v[196:199], v195 offset:39744
	ds_read_b128 v[200:203], v195 offset:40000
	ds_read_b32 v182, v127 offset:40256
	v_fmac_f32_dpp v58, v204, v76 quad_perm:[1,1,3,3] row_mask:0xf bank_mask:0xf
	v_fmac_f32_dpp v59, v204, v77 quad_perm:[1,1,3,3] row_mask:0xf bank_mask:0xf
	v_fmac_f32_dpp v60, v204, v78 quad_perm:[1,1,3,3] row_mask:0xf bank_mask:0xf
	v_fmac_f32_dpp v61, v204, v79 quad_perm:[1,1,3,3] row_mask:0xf bank_mask:0xf
	v_cndmask_b32_e64 v215, v215, v204, s[68:69]
	s_waitcnt lgkmcnt(6)
	v_mul_f32_e32 v204, v58, v92
	v_mul_f32_e32 v212, v58, v80
	v_fmac_f32_e32 v204, v59, v93
	v_fmac_f32_e32 v212, v59, v81
	v_fmac_f32_e32 v204, v60, v94
	v_fmac_f32_e32 v212, v60, v82
	v_fmac_f32_e32 v204, v61, v95
	v_fmac_f32_e32 v212, v61, v83
	v_mul_f32_e32 v208, v58, v84
	v_mul_f32_e32 v209, v59, v85
	v_mul_f32_e32 v210, v60, v86
	v_cndmask_b32_e64 v205, v204, v212, s[100:101]
	v_cndmask_b32_e64 v213, v212, v204, s[100:101]
	v_mul_f32_e32 v211, v61, v87
	v_add_f32_dpp v204, v205, v213 quad_perm:[1,0,3,2] row_mask:0xf bank_mask:0xf bound_ctrl:1
	v_fmac_f32_e32 v208, v88, v63
	v_fmac_f32_e32 v209, v89, v63
	v_add_f32_dpp v204, v204, v204 quad_perm:[2,3,0,1] row_mask:0xf bank_mask:0xf bound_ctrl:1
	v_fmac_f32_e32 v210, v90, v63
	v_fmac_f32_e32 v211, v91, v63
	v_add_f32_dpp v204, v204, v204 row_ror:4 row_mask:0xf bank_mask:0xf bound_ctrl:1
	ds_read_b128 v[64:67], v195 offset:40320
	ds_read_b128 v[68:71], v195 offset:40576
	v_add_f32_dpp v204, v204, v204 row_ror:8 row_mask:0xf bank_mask:0xf bound_ctrl:1
	ds_read_b128 v[72:75], v195 offset:40832
	ds_read_b128 v[76:79], v195 offset:41088
	ds_read_b128 v[80:83], v195 offset:41344
	ds_read_b32 v62, v127 offset:41600
	v_fmac_f32_dpp v208, v204, v96 quad_perm:[0,0,2,2] row_mask:0xf bank_mask:0xf
	v_fmac_f32_dpp v209, v204, v97 quad_perm:[0,0,2,2] row_mask:0xf bank_mask:0xf
	v_fmac_f32_dpp v210, v204, v98 quad_perm:[0,0,2,2] row_mask:0xf bank_mask:0xf
	v_fmac_f32_dpp v211, v204, v99 quad_perm:[0,0,2,2] row_mask:0xf bank_mask:0xf
	v_cndmask_b32_e64 v215, v215, v204, s[70:71]
	s_waitcnt lgkmcnt(6)
	v_mul_f32_e32 v204, v208, v112
	v_mul_f32_e32 v212, v208, v100
	v_fmac_f32_e32 v204, v209, v113
	v_fmac_f32_e32 v212, v209, v101
	v_fmac_f32_e32 v204, v210, v114
	v_fmac_f32_e32 v212, v210, v102
	v_fmac_f32_e32 v204, v211, v115
	v_fmac_f32_e32 v212, v211, v103
	v_mul_f32_e32 v58, v208, v104
	v_mul_f32_e32 v59, v209, v105
	v_mul_f32_e32 v60, v210, v106
	v_cndmask_b32_e64 v205, v212, v204, s[100:101]
	v_cndmask_b32_e64 v213, v204, v212, s[100:101]
	v_mul_f32_e32 v61, v211, v107
	v_add_f32_dpp v204, v205, v213 quad_perm:[1,0,3,2] row_mask:0xf bank_mask:0xf bound_ctrl:1
	v_fmac_f32_e32 v58, v108, v182
	v_fmac_f32_e32 v59, v109, v182
	v_add_f32_dpp v204, v204, v204 quad_perm:[2,3,0,1] row_mask:0xf bank_mask:0xf bound_ctrl:1
	v_fmac_f32_e32 v60, v110, v182
	v_fmac_f32_e32 v61, v111, v182
	v_add_f32_dpp v204, v204, v204 row_ror:4 row_mask:0xf bank_mask:0xf bound_ctrl:1
	ds_read_b128 v[84:87], v195 offset:41664
	ds_read_b128 v[88:91], v195 offset:41920
	v_add_f32_dpp v204, v204, v204 row_ror:8 row_mask:0xf bank_mask:0xf bound_ctrl:1
	ds_read_b128 v[92:95], v195 offset:42176
	ds_read_b128 v[96:99], v195 offset:42432
	ds_read_b128 v[100:103], v195 offset:42688
	ds_read_b32 v63, v127 offset:42944
	v_fmac_f32_dpp v58, v204, v196 quad_perm:[1,1,3,3] row_mask:0xf bank_mask:0xf
	v_fmac_f32_dpp v59, v204, v197 quad_perm:[1,1,3,3] row_mask:0xf bank_mask:0xf
	v_fmac_f32_dpp v60, v204, v198 quad_perm:[1,1,3,3] row_mask:0xf bank_mask:0xf
	v_fmac_f32_dpp v61, v204, v199 quad_perm:[1,1,3,3] row_mask:0xf bank_mask:0xf
	v_cndmask_b32_e64 v215, v215, v204, s[72:73]
	s_waitcnt lgkmcnt(6)
; #define LAS __attribute__((address_space(3)))
; template <int CTRL> __device__ __forceinline__ float dppf(float v) { return __int_as_float(__builtin_amdgcn_update_dpp(0, __float_as_int(v), CTRL, 0xf, 0xf, true)); }
; __device__ __forceinline__ float red16(float v) { v = red8(v); v += dppf<0x140>(v); return v; }
; __device__ __forceinline__ void scan_phase(const Args& a, LAS unsigned char* lds, const bf16* Z, const float* W, const bf16* Aa, const bf16* KK, float* Y, int tid, int lane, int wave) {
;     ...
;                 for (int q = 0; q < SCH; ++q) {
;                     const f32x4 wv = pw[q % 3], kv = pk[q % 3], av = pa[q % 3], bv = pb[q % 3], rv = pr[q % 3]; const float vv = pv[q % 3];
;                     if (q + 2 < SCH) {
;                         const LAS float* p = sb + (q + 2) * SROW; const int i = (q + 2) % 3;
;                         pw[i] = *(const LAS f32x4*)p; pk[i] = *(const LAS f32x4*)(p + 64); pa[i] = *(const LAS f32x4*)(p + 128); pb[i] = *(const LAS f32x4*)(p + 192); pr[i] = *(const LAS f32x4*)(p + 256);
;                         pv[i] = vb[(q + 2) * SROW];
;                     }
;                     f32x2 t2 = S01 * (f32x2){av.x, av.y}; t2 = S23 * (f32x2){av.z, av.w} + t2;
;                     float sa = t2.x + t2.y;
;                     sa += dppf<0xB1>(sa); yd += dppf<0xB1>(yd);
;                     sa += dppf<0x4E>(sa); yd += dppf<0x4E>(yd);
;                     sa += dppf<0x141>(sa); yd += dppf<0x141>(yd);
;                     sa += dppf<0x140>(sa); yd += dppf<0x140>(yd);
;                     if (q > 0) { if (q <= 16) ykA = (j == q - 1) ? yd : ykA; else ykB = (j == q - 17) ? yd : ykB; }
;                     const f32x2 u01 = S01 * (f32x2){wv.x, wv.y} + (f32x2){kv.x, kv.y} * vv, u23 = S23 * (f32x2){wv.z, wv.w} + (f32x2){kv.z, kv.w} * vv;
;                     S01 = u01 + (f32x2){bv.x, bv.y} * sa; S23 = u23 + (f32x2){bv.z, bv.w} * sa;
;                     f32x2 y2 = S01 * (f32x2){rv.x, rv.y}; y2 = S23 * (f32x2){rv.z, rv.w} + y2;
;                     yd = y2.x + y2.y;
;                 }
;                 yd = red16(yd); ykB = (j == 15) ? yd : ykB;
;                 yp[(size_t)(ch * SCH + j) * 512] = ykA;
;                 yp[(size_t)(ch * SCH + 16 + j) * 512] = ykB;
	v_mul_f32_e32 v204, v58, v72
	v_mul_f32_e32 v212, v58, v200
	v_fmac_f32_e32 v204, v59, v73
	v_fmac_f32_e32 v212, v59, v201
	v_fmac_f32_e32 v204, v60, v74
	v_fmac_f32_e32 v212, v60, v202
	v_fmac_f32_e32 v204, v61, v75
	v_fmac_f32_e32 v212, v61, v203
	v_mul_f32_e32 v208, v58, v64
	v_mul_f32_e32 v209, v59, v65
	v_mul_f32_e32 v210, v60, v66
	v_cndmask_b32_e64 v205, v204, v212, s[100:101]
	v_cndmask_b32_e64 v213, v212, v204, s[100:101]
	v_mul_f32_e32 v211, v61, v67
	v_add_f32_dpp v204, v205, v213 quad_perm:[1,0,3,2] row_mask:0xf bank_mask:0xf bound_ctrl:1
	v_fmac_f32_e32 v208, v68, v62
	v_fmac_f32_e32 v209, v69, v62
	v_add_f32_dpp v204, v204, v204 quad_perm:[2,3,0,1] row_mask:0xf bank_mask:0xf bound_ctrl:1
	v_fmac_f32_e32 v210, v70, v62
	v_fmac_f32_e32 v211, v71, v62
	v_add_f32_dpp v204, v204, v204 row_ror:4 row_mask:0xf bank_mask:0xf bound_ctrl:1
	s_nop 0
	s_nop 0
	v_add_f32_dpp v204, v204, v204 row_ror:8 row_mask:0xf bank_mask:0xf bound_ctrl:1
	s_nop 0
	s_nop 0
	v_fmac_f32_dpp v208, v204, v76 quad_perm:[0,0,2,2] row_mask:0xf bank_mask:0xf
	v_fmac_f32_dpp v209, v204, v77 quad_perm:[0,0,2,2] row_mask:0xf bank_mask:0xf
	v_fmac_f32_dpp v210, v204, v78 quad_perm:[0,0,2,2] row_mask:0xf bank_mask:0xf
	v_fmac_f32_dpp v211, v204, v79 quad_perm:[0,0,2,2] row_mask:0xf bank_mask:0xf
	v_cndmask_b32_e64 v215, v215, v204, s[74:75]
	s_waitcnt lgkmcnt(0)
	v_mul_f32_e32 v204, v208, v92
	v_mul_f32_e32 v212, v208, v80
	v_fmac_f32_e32 v204, v209, v93
	v_fmac_f32_e32 v212, v209, v81
	v_fmac_f32_e32 v204, v210, v94
	v_fmac_f32_e32 v212, v210, v82
	v_fmac_f32_e32 v204, v211, v95
	v_fmac_f32_e32 v212, v211, v83
	v_mul_f32_e32 v58, v208, v84
	v_mul_f32_e32 v59, v209, v85
	v_mul_f32_e32 v60, v210, v86
	v_cndmask_b32_e64 v205, v212, v204, s[100:101]
	v_cndmask_b32_e64 v213, v204, v212, s[100:101]
	v_mul_f32_e32 v61, v211, v87
	v_add_f32_dpp v204, v205, v213 quad_perm:[1,0,3,2] row_mask:0xf bank_mask:0xf bound_ctrl:1
	v_fmac_f32_e32 v58, v88, v63
	v_fmac_f32_e32 v59, v89, v63
	v_add_f32_dpp v204, v204, v204 quad_perm:[2,3,0,1] row_mask:0xf bank_mask:0xf bound_ctrl:1
	v_fmac_f32_e32 v60, v90, v63
	v_fmac_f32_e32 v61, v91, v63
	v_add_f32_dpp v204, v204, v204 row_ror:4 row_mask:0xf bank_mask:0xf bound_ctrl:1
	s_nop 0
	s_nop 0
	v_add_f32_dpp v204, v204, v204 row_ror:8 row_mask:0xf bank_mask:0xf bound_ctrl:1
	s_nop 0
	s_nop 0
	v_fmac_f32_dpp v58, v204, v96 quad_perm:[1,1,3,3] row_mask:0xf bank_mask:0xf
	v_fmac_f32_dpp v59, v204, v97 quad_perm:[1,1,3,3] row_mask:0xf bank_mask:0xf
	v_fmac_f32_dpp v60, v204, v98 quad_perm:[1,1,3,3] row_mask:0xf bank_mask:0xf
	v_fmac_f32_dpp v61, v204, v99 quad_perm:[1,1,3,3] row_mask:0xf bank_mask:0xf
	v_cndmask_b32_e64 v215, v215, v204, s[76:77]
	v_mul_f32_e32 v212, v58, v100
	v_fmac_f32_e32 v212, v59, v101
	v_fmac_f32_e32 v212, v60, v102
	v_fmac_f32_e32 v212, v61, v103
	v_lshl_add_u64 v[218:219], v[180:181], 0, s[4:5]
	s_nop 0
	v_add_f32_dpp v212, v212, v212 quad_perm:[1,0,3,2] row_mask:0xf bank_mask:0xf bound_ctrl:1
	v_add_co_u32_e32 v220, vcc, 0x5800000, v218
	s_nop 1
	v_add_f32_dpp v212, v212, v212 quad_perm:[2,3,0,1] row_mask:0xf bank_mask:0xf bound_ctrl:1
	v_addc_co_u32_e32 v221, vcc, 0, v219, vcc
	s_nop 0
	v_add_f32_dpp v212, v212, v212 row_half_mirror row_mask:0xf bank_mask:0xf bound_ctrl:1
	v_add_co_u32_e32 v218, vcc, 0x5808000, v218
	s_nop 1
	v_add_f32_dpp v212, v212, v212 row_mirror row_mask:0xf bank_mask:0xf bound_ctrl:1
	v_addc_co_u32_e32 v219, vcc, 0, v219, vcc
	v_cndmask_b32_e64 v215, v215, v212, s[96:97]
	global_store_dword v[220:221], v214, off
	global_store_dword v[218:219], v215, off
	s_branch .LBB0_224
